# stack: rolling-window residual epilogues (P5 W16, P7/P11/P13 W6) + first 2 MFMAs before block barrier
# baseline (speedup 1.0000x reference)
; __device__ __forceinline__ unsigned cvt_pk_bf16(float lo, float hi) { return ::cvtpk(lo, hi); }
;     __device__ __forceinline__ void operator()(const f32x4 (&acc)[2][2][4][2], const Unit& u, int wr, int wc, int fr, int fq, int) const {
;         const int row0 = u.pm * BM + wr * 64 + fr, col0 = u.pn * BM + wc * 32 + 4 * fq;
; #pragma unroll
;         for (int ai = 0; ai < 2; ++ai)
; #pragma unroll
;             for (int m = 0; m < 4; ++m) { const int row = row0 + ai * HALF + m * 16; const size_t off = (size_t)row * 2048 + col0; float s = 0.f;
; #pragma unroll
;                 for (int bj = 0; bj < 2; ++bj)
; #pragma unroll
;                     for (int n = 0; n < 2; ++n) { const size_t o2 = off + bj * HALF + n * 16; f32x4 bs;
;                         if (MODE == 0) bs = __builtin_nontemporal_load((const f32x4*)(base + o2));
;                         else { const u32x2 b2 = *(const u32x2*)(xb + o2); bs[0] = __builtin_bit_cast(float, b2.x << 16); bs[1] = __builtin_bit_cast(float, b2.x & 0xffff0000u); bs[2] = __builtin_bit_cast(float, b2.y << 16); bs[3] = __builtin_bit_cast(float, b2.y & 0xffff0000u); }
;                         const f32x4 o = bs + acc[ai][bj][m][n];
;                         if (MODE == 2) __builtin_nontemporal_store(o, (f32x4*)(out + o2));
;                         else { s += (o[0] * o[0] + o[1] * o[1]) + (o[2] * o[2] + o[3] * o[3]); u32x2 w; w.x = cvt_pk_bf16(o[0], o[1]); w.y = cvt_pk_bf16(o[2], o[3]); *(u32x2*)(xb + o2) = w; } }
;                 if (MODE != 2) { s += __shfl_xor(s, 16); s += __shfl_xor(s, 32); if (fq == 0) ssq[(size_t)row * 32 + u.pn * 4 + wc] = s; } }
.LBB0_1083:
	v_xor_b32_e32 v145, 16, v175
	v_cmp_lt_i32_e32 vcc, v145, v177
	v_lshl_add_u32 v144, s46, 8, v148
	v_lshl_or_b32 v142, s0, 8, v150
	v_cndmask_b32_e32 v145, v175, v145, vcc
	v_lshlrev_b32_e32 v155, 2, v145
	v_xor_b32_e32 v145, 32, v175
	v_cmp_lt_i32_e32 vcc, v145, v177
	v_ashrrev_i32_e32 v143, 31, v142
	s_lshl_b32 s18, s0, 2
	v_cndmask_b32_e32 v145, v175, v145, vcc
	v_lshlrev_b32_e32 v154, 2, v145
	v_ashrrev_i32_e32 v145, 31, v144
	v_lshlrev_b64 v[146:147], 12, v[144:145]
	v_lshl_add_u64 v[146:147], s[80:81], 0, v[146:147]
	v_lshl_add_u64 v[146:147], v[142:143], 1, v[146:147]
	s_nop 4
	v_subrev_u32_e32 v179, s80, v146
	s_nop 1
	global_load_dwordx2 v[160:161], v179, s[80:81]
	global_load_dwordx2 v[162:163], v179, s[80:81] offset:32
	global_load_dwordx2 v[164:165], v179, s[80:81] offset:256
	global_load_dwordx2 v[166:167], v179, s[80:81] offset:288
	v_add_u32_e32 v180, 0x10000, v179
	global_load_dwordx2 v[168:169], v180, s[80:81]
	global_load_dwordx2 v[170:171], v180, s[80:81] offset:32
	s_waitcnt vmcnt(5)
	s_nop 1
	v_mov_b32_e32 v156, v160
	v_mov_b32_e32 v157, v161
	global_load_dwordx2 v[160:161], v180, s[80:81] offset:256
	s_ashr_i32 s19, s18, 31
	v_lshlrev_b32_e32 v158, 16, v156
	v_and_b32_e32 v159, 0xffff0000, v156
	v_lshlrev_b32_e32 v156, 16, v157
	v_and_b32_e32 v157, 0xffff0000, v157
	v_pk_add_f32 v[124:125], v[124:125], v[158:159]
	v_pk_add_f32 v[126:127], v[126:127], v[156:157]
	v_mul_f32_e32 v156, v125, v125
	v_fmac_f32_e32 v156, v124, v124
	v_cvt_pk_bf16_f32 v124, v124, v125
	v_cvt_pk_bf16_f32 v125, v126, v127
	global_store_dwordx2 v[146:147], v[124:125], off
	s_waitcnt vmcnt(6)
	s_nop 1
	v_mov_b32_e32 v124, v162
	v_mov_b32_e32 v125, v163
	global_load_dwordx2 v[162:163], v180, s[80:81] offset:288
	v_mul_f32_e32 v157, v127, v127
	v_fmac_f32_e32 v157, v126, v126
	v_add_f32_e32 v156, v156, v157
	v_lshlrev_b32_e32 v126, 16, v124
	v_and_b32_e32 v127, 0xffff0000, v124
	v_lshlrev_b32_e32 v124, 16, v125
	v_and_b32_e32 v125, 0xffff0000, v125
	v_pk_add_f32 v[120:121], v[120:121], v[126:127]
	v_pk_add_f32 v[122:123], v[122:123], v[124:125]
	v_mul_f32_e32 v124, v121, v121
	v_fmac_f32_e32 v124, v120, v120
	v_cvt_pk_bf16_f32 v120, v120, v121
	v_cvt_pk_bf16_f32 v121, v122, v123
	global_store_dwordx2 v[146:147], v[120:121], off offset:32
	s_waitcnt vmcnt(7)
	s_nop 1
	v_mov_b32_e32 v120, v164
	v_mov_b32_e32 v121, v165
	v_add_u32_e32 v180, 0x20000, v179
	global_load_dwordx2 v[164:165], v180, s[80:81]
	v_mul_f32_e32 v125, v123, v123
	v_fmac_f32_e32 v125, v122, v122
	v_add_f32_e32 v124, v124, v125
	v_add_f32_e32 v124, v156, v124
	v_lshlrev_b32_e32 v122, 16, v120
	v_and_b32_e32 v123, 0xffff0000, v120
	v_lshlrev_b32_e32 v120, 16, v121
	v_and_b32_e32 v121, 0xffff0000, v121
	v_pk_add_f32 v[116:117], v[116:117], v[122:123]
	v_pk_add_f32 v[118:119], v[118:119], v[120:121]
	v_mul_f32_e32 v120, v117, v117
	v_fmac_f32_e32 v120, v116, v116
	v_cvt_pk_bf16_f32 v116, v116, v117
	v_cvt_pk_bf16_f32 v117, v118, v119
	global_store_dwordx2 v[146:147], v[116:117], off offset:256
	s_waitcnt vmcnt(8)
	s_nop 1
	v_mov_b32_e32 v116, v166
	v_mov_b32_e32 v117, v167
	global_load_dwordx2 v[166:167], v180, s[80:81] offset:32
	v_mul_f32_e32 v121, v119, v119
	v_fmac_f32_e32 v121, v118, v118
	v_add_f32_e32 v120, v120, v121
	v_add_f32_e32 v120, v124, v120
	v_lshlrev_b32_e32 v118, 16, v116
	v_and_b32_e32 v119, 0xffff0000, v116
	v_lshlrev_b32_e32 v116, 16, v117
	v_and_b32_e32 v117, 0xffff0000, v117
	v_pk_add_f32 v[114:115], v[114:115], v[116:117]
	v_pk_add_f32 v[112:113], v[112:113], v[118:119]
	v_mul_f32_e32 v117, v115, v115
	v_mul_f32_e32 v116, v113, v113
	v_fmac_f32_e32 v116, v112, v112
	v_fmac_f32_e32 v117, v114, v114
	v_add_f32_e32 v116, v116, v117
	v_add_f32_e32 v116, v120, v116
	v_cvt_pk_bf16_f32 v112, v112, v113
	v_cvt_pk_bf16_f32 v113, v114, v115
	global_store_dwordx2 v[146:147], v[112:113], off offset:288
	ds_bpermute_b32 v112, v155, v116
	s_waitcnt lgkmcnt(0)
	v_add_f32_e32 v112, v116, v112
	ds_bpermute_b32 v113, v154, v112
	s_and_saveexec_b64 s[20:21], s[8:9]
	s_cbranch_execz .LBB0_1085
	v_readlane_b32 s22, v237, 48
	s_waitcnt lgkmcnt(0)
	v_add_f32_e32 v114, v112, v113
	v_lshlrev_b64 v[112:113], 7, v[144:145]
	v_readlane_b32 s23, v237, 49
	s_lshl_b32 s0, s34, 2
	s_nop 0
	v_lshl_add_u64 v[112:113], s[22:23], 0, v[112:113]
	v_lshl_add_u64 v[112:113], s[18:19], 2, v[112:113]
	v_lshl_add_u64 v[112:113], v[112:113], 0, s[0:1]
	global_store_dword v[112:113], v114, off
; __device__ __forceinline__ unsigned cvt_pk_bf16(float lo, float hi) { return ::cvtpk(lo, hi); }
;     __device__ __forceinline__ void operator()(const f32x4 (&acc)[2][2][4][2], const Unit& u, int wr, int wc, int fr, int fq, int) const {
;         const int row0 = u.pm * BM + wr * 64 + fr, col0 = u.pn * BM + wc * 32 + 4 * fq;
; #pragma unroll
;         for (int ai = 0; ai < 2; ++ai)
; #pragma unroll
;             for (int m = 0; m < 4; ++m) { const int row = row0 + ai * HALF + m * 16; const size_t off = (size_t)row * 2048 + col0; float s = 0.f;
; #pragma unroll
;                 for (int bj = 0; bj < 2; ++bj)
; #pragma unroll
;                     for (int n = 0; n < 2; ++n) { const size_t o2 = off + bj * HALF + n * 16; f32x4 bs;
;                         if (MODE == 0) bs = __builtin_nontemporal_load((const f32x4*)(base + o2));
;                         else { const u32x2 b2 = *(const u32x2*)(xb + o2); bs[0] = __builtin_bit_cast(float, b2.x << 16); bs[1] = __builtin_bit_cast(float, b2.x & 0xffff0000u); bs[2] = __builtin_bit_cast(float, b2.y << 16); bs[3] = __builtin_bit_cast(float, b2.y & 0xffff0000u); }
;                         const f32x4 o = bs + acc[ai][bj][m][n];
;                         if (MODE == 2) __builtin_nontemporal_store(o, (f32x4*)(out + o2));
;                         else { s += (o[0] * o[0] + o[1] * o[1]) + (o[2] * o[2] + o[3] * o[3]); u32x2 w; w.x = cvt_pk_bf16(o[0], o[1]); w.y = cvt_pk_bf16(o[2], o[3]); *(u32x2*)(xb + o2) = w; } }
;                 if (MODE != 2) { s += __shfl_xor(s, 16); s += __shfl_xor(s, 32); if (fq == 0) ssq[(size_t)row * 32 + u.pn * 4 + wc] = s; } }
.LBB0_1085:
	s_or_b64 exec, exec, s[20:21]
	v_or_b32_e32 v112, 16, v144
	s_waitcnt lgkmcnt(0)
	v_ashrrev_i32_e32 v113, 31, v112
	v_lshlrev_b64 v[114:115], 12, v[112:113]
	v_lshl_add_u64 v[114:115], s[80:81], 0, v[114:115]
	v_lshl_add_u64 v[114:115], v[142:143], 1, v[114:115]
	s_waitcnt vmcnt(9)
	s_nop 1
	v_mov_b32_e32 v116, v168
	v_mov_b32_e32 v117, v169
	global_load_dwordx2 v[168:169], v180, s[80:81] offset:256
	v_lshlrev_b32_e32 v118, 16, v116
	v_and_b32_e32 v119, 0xffff0000, v116
	v_lshlrev_b32_e32 v116, 16, v117
	v_and_b32_e32 v117, 0xffff0000, v117
	v_pk_add_f32 v[108:109], v[108:109], v[118:119]
	v_pk_add_f32 v[110:111], v[110:111], v[116:117]
	v_mul_f32_e32 v116, v109, v109
	v_fmac_f32_e32 v116, v108, v108
	v_cvt_pk_bf16_f32 v108, v108, v109
	v_cvt_pk_bf16_f32 v109, v110, v111
	global_store_dwordx2 v[114:115], v[108:109], off
	s_waitcnt vmcnt(10)
	s_nop 1
	v_mov_b32_e32 v108, v170
	v_mov_b32_e32 v109, v171
	global_load_dwordx2 v[170:171], v180, s[80:81] offset:288
	v_mul_f32_e32 v117, v111, v111
	v_fmac_f32_e32 v117, v110, v110
	v_add_f32_e32 v116, v116, v117
	v_lshlrev_b32_e32 v110, 16, v108
	v_and_b32_e32 v111, 0xffff0000, v108
	v_lshlrev_b32_e32 v108, 16, v109
	v_and_b32_e32 v109, 0xffff0000, v109
	v_pk_add_f32 v[104:105], v[104:105], v[110:111]
	v_pk_add_f32 v[106:107], v[106:107], v[108:109]
	v_mul_f32_e32 v108, v105, v105
	v_fmac_f32_e32 v108, v104, v104
	v_cvt_pk_bf16_f32 v104, v104, v105
	v_cvt_pk_bf16_f32 v105, v106, v107
	global_store_dwordx2 v[114:115], v[104:105], off offset:32
	s_waitcnt vmcnt(11)
	s_nop 1
	v_mov_b32_e32 v104, v160
	v_mov_b32_e32 v105, v161
	v_add_u32_e32 v180, 0x30000, v179
	global_load_dwordx2 v[160:161], v180, s[80:81]
	v_mul_f32_e32 v109, v107, v107
	v_fmac_f32_e32 v109, v106, v106
	v_add_f32_e32 v108, v108, v109
	v_add_f32_e32 v108, v116, v108
	v_lshlrev_b32_e32 v106, 16, v104
	v_and_b32_e32 v107, 0xffff0000, v104
	v_lshlrev_b32_e32 v104, 16, v105
	v_and_b32_e32 v105, 0xffff0000, v105
	v_pk_add_f32 v[100:101], v[100:101], v[106:107]
	v_pk_add_f32 v[102:103], v[102:103], v[104:105]
	v_mul_f32_e32 v104, v101, v101
	v_fmac_f32_e32 v104, v100, v100
	v_cvt_pk_bf16_f32 v100, v100, v101
	v_cvt_pk_bf16_f32 v101, v102, v103
	global_store_dwordx2 v[114:115], v[100:101], off offset:256
	s_waitcnt vmcnt(11)
	s_nop 1
	v_mov_b32_e32 v100, v162
	v_mov_b32_e32 v101, v163
	global_load_dwordx2 v[162:163], v180, s[80:81] offset:32
	v_mul_f32_e32 v105, v103, v103
	v_fmac_f32_e32 v105, v102, v102
	v_add_f32_e32 v104, v104, v105
	v_add_f32_e32 v104, v108, v104
	v_lshlrev_b32_e32 v102, 16, v100
	v_and_b32_e32 v103, 0xffff0000, v100
	v_lshlrev_b32_e32 v100, 16, v101
	v_and_b32_e32 v101, 0xffff0000, v101
	v_pk_add_f32 v[98:99], v[98:99], v[100:101]
	v_pk_add_f32 v[96:97], v[96:97], v[102:103]
	v_mul_f32_e32 v101, v99, v99
	v_mul_f32_e32 v100, v97, v97
	v_fmac_f32_e32 v100, v96, v96
	v_fmac_f32_e32 v101, v98, v98
	v_add_f32_e32 v100, v100, v101
	v_add_f32_e32 v100, v104, v100
	v_cvt_pk_bf16_f32 v96, v96, v97
	v_cvt_pk_bf16_f32 v97, v98, v99
	global_store_dwordx2 v[114:115], v[96:97], off offset:288
	ds_bpermute_b32 v96, v155, v100
	s_waitcnt lgkmcnt(0)
	v_add_f32_e32 v96, v100, v96
	ds_bpermute_b32 v97, v154, v96
	s_and_saveexec_b64 s[20:21], s[8:9]
	s_cbranch_execz .LBB0_1087
	v_readlane_b32 s22, v237, 48
	s_waitcnt lgkmcnt(0)
	v_add_f32_e32 v98, v96, v97
	v_lshlrev_b64 v[96:97], 7, v[112:113]
	v_readlane_b32 s23, v237, 49
	s_lshl_b32 s0, s34, 2
	s_nop 0
	v_lshl_add_u64 v[96:97], s[22:23], 0, v[96:97]
	v_lshl_add_u64 v[96:97], s[18:19], 2, v[96:97]
	v_lshl_add_u64 v[96:97], v[96:97], 0, s[0:1]
	global_store_dword v[96:97], v98, off
.LBB0_1087:
	s_or_b64 exec, exec, s[20:21]
	v_or_b32_e32 v96, 32, v144
	s_waitcnt lgkmcnt(0)
	v_ashrrev_i32_e32 v97, 31, v96
	v_lshlrev_b64 v[98:99], 12, v[96:97]
	v_lshl_add_u64 v[98:99], s[80:81], 0, v[98:99]
	v_lshl_add_u64 v[98:99], v[142:143], 1, v[98:99]
	s_waitcnt vmcnt(11)
	s_nop 1
	v_mov_b32_e32 v100, v164
	v_mov_b32_e32 v101, v165
	global_load_dwordx2 v[164:165], v180, s[80:81] offset:256
	v_lshlrev_b32_e32 v102, 16, v100
	v_and_b32_e32 v103, 0xffff0000, v100
	v_lshlrev_b32_e32 v100, 16, v101
	v_and_b32_e32 v101, 0xffff0000, v101
	v_pk_add_f32 v[92:93], v[92:93], v[102:103]
	v_pk_add_f32 v[94:95], v[94:95], v[100:101]
	v_mul_f32_e32 v100, v93, v93
	v_fmac_f32_e32 v100, v92, v92
	v_cvt_pk_bf16_f32 v92, v92, v93
	v_cvt_pk_bf16_f32 v93, v94, v95
	global_store_dwordx2 v[98:99], v[92:93], off
	s_waitcnt vmcnt(11)
	s_nop 1
	v_mov_b32_e32 v92, v166
	v_mov_b32_e32 v93, v167
	global_load_dwordx2 v[166:167], v180, s[80:81] offset:288
	v_mul_f32_e32 v101, v95, v95
	v_fmac_f32_e32 v101, v94, v94
	v_add_f32_e32 v100, v100, v101
	v_lshlrev_b32_e32 v94, 16, v92
	v_and_b32_e32 v95, 0xffff0000, v92
	v_lshlrev_b32_e32 v92, 16, v93
	v_and_b32_e32 v93, 0xffff0000, v93
	v_pk_add_f32 v[88:89], v[88:89], v[94:95]
	v_pk_add_f32 v[90:91], v[90:91], v[92:93]
	v_mul_f32_e32 v92, v89, v89
	v_fmac_f32_e32 v92, v88, v88
	v_cvt_pk_bf16_f32 v88, v88, v89
	v_cvt_pk_bf16_f32 v89, v90, v91
	global_store_dwordx2 v[98:99], v[88:89], off offset:32
	s_waitcnt vmcnt(11)
	s_nop 1
	v_mov_b32_e32 v88, v168
	v_mov_b32_e32 v89, v169
	v_add_u32_e32 v180, 0x80000, v179
	global_load_dwordx2 v[168:169], v180, s[80:81]
	v_mul_f32_e32 v93, v91, v91
	v_fmac_f32_e32 v93, v90, v90
	v_add_f32_e32 v92, v92, v93
	v_add_f32_e32 v92, v100, v92
	v_lshlrev_b32_e32 v90, 16, v88
	v_and_b32_e32 v91, 0xffff0000, v88
	v_lshlrev_b32_e32 v88, 16, v89
	v_and_b32_e32 v89, 0xffff0000, v89
	v_pk_add_f32 v[84:85], v[84:85], v[90:91]
	v_pk_add_f32 v[86:87], v[86:87], v[88:89]
	v_mul_f32_e32 v88, v85, v85
	v_fmac_f32_e32 v88, v84, v84
	v_cvt_pk_bf16_f32 v84, v84, v85
	v_cvt_pk_bf16_f32 v85, v86, v87
	global_store_dwordx2 v[98:99], v[84:85], off offset:256
	s_waitcnt vmcnt(11)
	s_nop 1
	v_mov_b32_e32 v84, v170
	v_mov_b32_e32 v85, v171
	global_load_dwordx2 v[170:171], v180, s[80:81] offset:32
	v_mul_f32_e32 v89, v87, v87
	v_fmac_f32_e32 v89, v86, v86
	v_add_f32_e32 v88, v88, v89
	v_add_f32_e32 v88, v92, v88
	v_lshlrev_b32_e32 v86, 16, v84
	v_and_b32_e32 v87, 0xffff0000, v84
	v_lshlrev_b32_e32 v84, 16, v85
	v_and_b32_e32 v85, 0xffff0000, v85
	v_pk_add_f32 v[82:83], v[82:83], v[84:85]
	v_pk_add_f32 v[80:81], v[80:81], v[86:87]
	v_mul_f32_e32 v85, v83, v83
	v_mul_f32_e32 v84, v81, v81
	v_fmac_f32_e32 v84, v80, v80
	v_fmac_f32_e32 v85, v82, v82
	v_add_f32_e32 v84, v84, v85
	v_add_f32_e32 v84, v88, v84
	v_cvt_pk_bf16_f32 v80, v80, v81
	v_cvt_pk_bf16_f32 v81, v82, v83
	global_store_dwordx2 v[98:99], v[80:81], off offset:288
	ds_bpermute_b32 v80, v155, v84
	s_waitcnt lgkmcnt(0)
	v_add_f32_e32 v80, v84, v80
	ds_bpermute_b32 v81, v154, v80
	s_and_saveexec_b64 s[20:21], s[8:9]
	s_cbranch_execz .LBB0_1089
; __device__ __forceinline__ unsigned cvt_pk_bf16(float lo, float hi) { return ::cvtpk(lo, hi); }
;     __device__ __forceinline__ void operator()(const f32x4 (&acc)[2][2][4][2], const Unit& u, int wr, int wc, int fr, int fq, int) const {
;         const int row0 = u.pm * BM + wr * 64 + fr, col0 = u.pn * BM + wc * 32 + 4 * fq;
; #pragma unroll
;         for (int ai = 0; ai < 2; ++ai)
; #pragma unroll
;             for (int m = 0; m < 4; ++m) { const int row = row0 + ai * HALF + m * 16; const size_t off = (size_t)row * 2048 + col0; float s = 0.f;
; #pragma unroll
;                 for (int bj = 0; bj < 2; ++bj)
; #pragma unroll
;                     for (int n = 0; n < 2; ++n) { const size_t o2 = off + bj * HALF + n * 16; f32x4 bs;
;                         if (MODE == 0) bs = __builtin_nontemporal_load((const f32x4*)(base + o2));
;                         else { const u32x2 b2 = *(const u32x2*)(xb + o2); bs[0] = __builtin_bit_cast(float, b2.x << 16); bs[1] = __builtin_bit_cast(float, b2.x & 0xffff0000u); bs[2] = __builtin_bit_cast(float, b2.y << 16); bs[3] = __builtin_bit_cast(float, b2.y & 0xffff0000u); }
;                         const f32x4 o = bs + acc[ai][bj][m][n];
;                         if (MODE == 2) __builtin_nontemporal_store(o, (f32x4*)(out + o2));
;                         else { s += (o[0] * o[0] + o[1] * o[1]) + (o[2] * o[2] + o[3] * o[3]); u32x2 w; w.x = cvt_pk_bf16(o[0], o[1]); w.y = cvt_pk_bf16(o[2], o[3]); *(u32x2*)(xb + o2) = w; } }
;                 if (MODE != 2) { s += __shfl_xor(s, 16); s += __shfl_xor(s, 32); if (fq == 0) ssq[(size_t)row * 32 + u.pn * 4 + wc] = s; } }
	v_readlane_b32 s22, v237, 48
	s_waitcnt lgkmcnt(0)
	v_add_f32_e32 v82, v80, v81
	v_lshlrev_b64 v[80:81], 7, v[96:97]
	v_readlane_b32 s23, v237, 49
	s_lshl_b32 s0, s34, 2
	s_nop 0
	v_lshl_add_u64 v[80:81], s[22:23], 0, v[80:81]
	v_lshl_add_u64 v[80:81], s[18:19], 2, v[80:81]
	v_lshl_add_u64 v[80:81], v[80:81], 0, s[0:1]
	global_store_dword v[80:81], v82, off
.LBB0_1089:
	s_or_b64 exec, exec, s[20:21]
	v_or_b32_e32 v80, 48, v144
	s_waitcnt lgkmcnt(0)
	v_ashrrev_i32_e32 v81, 31, v80
	v_lshlrev_b64 v[82:83], 12, v[80:81]
	v_lshl_add_u64 v[82:83], s[80:81], 0, v[82:83]
	v_lshl_add_u64 v[82:83], v[142:143], 1, v[82:83]
	s_waitcnt vmcnt(11)
	s_nop 1
	v_mov_b32_e32 v84, v160
	v_mov_b32_e32 v85, v161
	global_load_dwordx2 v[160:161], v180, s[80:81] offset:256
	v_lshlrev_b32_e32 v86, 16, v84
	v_and_b32_e32 v87, 0xffff0000, v84
	v_lshlrev_b32_e32 v84, 16, v85
	v_and_b32_e32 v85, 0xffff0000, v85
	v_pk_add_f32 v[76:77], v[76:77], v[86:87]
	v_pk_add_f32 v[78:79], v[78:79], v[84:85]
	v_mul_f32_e32 v84, v77, v77
	v_fmac_f32_e32 v84, v76, v76
	v_cvt_pk_bf16_f32 v76, v76, v77
	v_cvt_pk_bf16_f32 v77, v78, v79
	global_store_dwordx2 v[82:83], v[76:77], off
	s_waitcnt vmcnt(11)
	s_nop 1
	v_mov_b32_e32 v76, v162
	v_mov_b32_e32 v77, v163
	global_load_dwordx2 v[162:163], v180, s[80:81] offset:288
	v_mul_f32_e32 v85, v79, v79
	v_fmac_f32_e32 v85, v78, v78
	v_add_f32_e32 v84, v84, v85
	v_lshlrev_b32_e32 v78, 16, v76
	v_and_b32_e32 v79, 0xffff0000, v76
	v_lshlrev_b32_e32 v76, 16, v77
	v_and_b32_e32 v77, 0xffff0000, v77
	v_pk_add_f32 v[72:73], v[72:73], v[78:79]
	v_pk_add_f32 v[74:75], v[74:75], v[76:77]
	v_mul_f32_e32 v76, v73, v73
	v_fmac_f32_e32 v76, v72, v72
	v_cvt_pk_bf16_f32 v72, v72, v73
	v_cvt_pk_bf16_f32 v73, v74, v75
	global_store_dwordx2 v[82:83], v[72:73], off offset:32
	s_waitcnt vmcnt(11)
	s_nop 1
	v_mov_b32_e32 v72, v164
	v_mov_b32_e32 v73, v165
	v_add_u32_e32 v180, 0x90000, v179
	global_load_dwordx2 v[164:165], v180, s[80:81]
	v_mul_f32_e32 v77, v75, v75
	v_fmac_f32_e32 v77, v74, v74
	v_add_f32_e32 v76, v76, v77
	v_add_f32_e32 v76, v84, v76
	v_lshlrev_b32_e32 v74, 16, v72
	v_and_b32_e32 v75, 0xffff0000, v72
	v_lshlrev_b32_e32 v72, 16, v73
	v_and_b32_e32 v73, 0xffff0000, v73
	v_pk_add_f32 v[68:69], v[68:69], v[74:75]
	v_pk_add_f32 v[70:71], v[70:71], v[72:73]
	v_mul_f32_e32 v72, v69, v69
	v_fmac_f32_e32 v72, v68, v68
	v_cvt_pk_bf16_f32 v68, v68, v69
	v_cvt_pk_bf16_f32 v69, v70, v71
	global_store_dwordx2 v[82:83], v[68:69], off offset:256
	s_waitcnt vmcnt(11)
	s_nop 1
	v_mov_b32_e32 v68, v166
	v_mov_b32_e32 v69, v167
	global_load_dwordx2 v[166:167], v180, s[80:81] offset:32
	v_mul_f32_e32 v73, v71, v71
	v_fmac_f32_e32 v73, v70, v70
	v_add_f32_e32 v72, v72, v73
	v_add_f32_e32 v72, v76, v72
	v_lshlrev_b32_e32 v70, 16, v68
	v_and_b32_e32 v71, 0xffff0000, v68
	v_lshlrev_b32_e32 v68, 16, v69
	v_and_b32_e32 v69, 0xffff0000, v69
	v_pk_add_f32 v[66:67], v[66:67], v[68:69]
	v_pk_add_f32 v[64:65], v[64:65], v[70:71]
	v_mul_f32_e32 v69, v67, v67
	v_mul_f32_e32 v68, v65, v65
	v_fmac_f32_e32 v68, v64, v64
	v_fmac_f32_e32 v69, v66, v66
	v_add_f32_e32 v68, v68, v69
	v_add_f32_e32 v68, v72, v68
	v_cvt_pk_bf16_f32 v64, v64, v65
	v_cvt_pk_bf16_f32 v65, v66, v67
	global_store_dwordx2 v[82:83], v[64:65], off offset:288
	ds_bpermute_b32 v64, v155, v68
	s_waitcnt lgkmcnt(0)
	v_add_f32_e32 v64, v68, v64
	ds_bpermute_b32 v65, v154, v64
	s_and_saveexec_b64 s[20:21], s[8:9]
	s_cbranch_execz .LBB0_1091
	v_readlane_b32 s22, v237, 48
	s_waitcnt lgkmcnt(0)
	v_add_f32_e32 v66, v64, v65
	v_lshlrev_b64 v[64:65], 7, v[80:81]
	v_readlane_b32 s23, v237, 49
	s_lshl_b32 s0, s34, 2
	s_nop 0
	v_lshl_add_u64 v[64:65], s[22:23], 0, v[64:65]
	v_lshl_add_u64 v[64:65], s[18:19], 2, v[64:65]
	v_lshl_add_u64 v[64:65], v[64:65], 0, s[0:1]
	global_store_dword v[64:65], v66, off
.LBB0_1091:
	s_or_b64 exec, exec, s[20:21]
	v_add_u32_e32 v64, 0x80, v144
	s_waitcnt lgkmcnt(0)
	v_ashrrev_i32_e32 v65, 31, v64
	v_lshlrev_b64 v[66:67], 12, v[64:65]
	v_lshl_add_u64 v[66:67], s[80:81], 0, v[66:67]
	v_lshl_add_u64 v[66:67], v[142:143], 1, v[66:67]
	s_waitcnt vmcnt(11)
	s_nop 1
	v_mov_b32_e32 v68, v168
	v_mov_b32_e32 v69, v169
	global_load_dwordx2 v[168:169], v180, s[80:81] offset:256
	v_lshlrev_b32_e32 v70, 16, v68
	v_and_b32_e32 v71, 0xffff0000, v68
	v_lshlrev_b32_e32 v68, 16, v69
	v_and_b32_e32 v69, 0xffff0000, v69
	v_pk_add_f32 v[60:61], v[60:61], v[70:71]
	v_pk_add_f32 v[62:63], v[62:63], v[68:69]
	v_mul_f32_e32 v68, v61, v61
	v_fmac_f32_e32 v68, v60, v60
	v_cvt_pk_bf16_f32 v60, v60, v61
	v_cvt_pk_bf16_f32 v61, v62, v63
	global_store_dwordx2 v[66:67], v[60:61], off
	s_waitcnt vmcnt(11)
	s_nop 1
	v_mov_b32_e32 v60, v170
	v_mov_b32_e32 v61, v171
	global_load_dwordx2 v[170:171], v180, s[80:81] offset:288
	v_mul_f32_e32 v69, v63, v63
	v_fmac_f32_e32 v69, v62, v62
	v_add_f32_e32 v68, v68, v69
	v_lshlrev_b32_e32 v62, 16, v60
	v_and_b32_e32 v63, 0xffff0000, v60
	v_lshlrev_b32_e32 v60, 16, v61
	v_and_b32_e32 v61, 0xffff0000, v61
	v_pk_add_f32 v[56:57], v[56:57], v[62:63]
	v_pk_add_f32 v[58:59], v[58:59], v[60:61]
	v_mul_f32_e32 v60, v57, v57
	v_fmac_f32_e32 v60, v56, v56
	v_cvt_pk_bf16_f32 v56, v56, v57
	v_cvt_pk_bf16_f32 v57, v58, v59
	global_store_dwordx2 v[66:67], v[56:57], off offset:32
	s_waitcnt vmcnt(11)
	s_nop 1
	v_mov_b32_e32 v56, v160
	v_mov_b32_e32 v57, v161
	v_add_u32_e32 v180, 0xa0000, v179
	global_load_dwordx2 v[160:161], v180, s[80:81]
	v_mul_f32_e32 v61, v59, v59
	v_fmac_f32_e32 v61, v58, v58
	v_add_f32_e32 v60, v60, v61
	v_add_f32_e32 v60, v68, v60
	v_lshlrev_b32_e32 v58, 16, v56
	v_and_b32_e32 v59, 0xffff0000, v56
	v_lshlrev_b32_e32 v56, 16, v57
	v_and_b32_e32 v57, 0xffff0000, v57
	v_pk_add_f32 v[52:53], v[52:53], v[58:59]
	v_pk_add_f32 v[54:55], v[54:55], v[56:57]
	v_mul_f32_e32 v56, v53, v53
	v_fmac_f32_e32 v56, v52, v52
	v_cvt_pk_bf16_f32 v52, v52, v53
	v_cvt_pk_bf16_f32 v53, v54, v55
	global_store_dwordx2 v[66:67], v[52:53], off offset:256
	s_waitcnt vmcnt(11)
	s_nop 1
	v_mov_b32_e32 v52, v162
	v_mov_b32_e32 v53, v163
	global_load_dwordx2 v[162:163], v180, s[80:81] offset:32
	v_mul_f32_e32 v57, v55, v55
	v_fmac_f32_e32 v57, v54, v54
	v_add_f32_e32 v56, v56, v57
	v_add_f32_e32 v56, v60, v56
	v_lshlrev_b32_e32 v54, 16, v52
	v_and_b32_e32 v55, 0xffff0000, v52
	v_lshlrev_b32_e32 v52, 16, v53
	v_and_b32_e32 v53, 0xffff0000, v53
	v_pk_add_f32 v[50:51], v[50:51], v[52:53]
	v_pk_add_f32 v[48:49], v[48:49], v[54:55]
	v_mul_f32_e32 v53, v51, v51
	v_mul_f32_e32 v52, v49, v49
	v_fmac_f32_e32 v52, v48, v48
	v_fmac_f32_e32 v53, v50, v50
	v_add_f32_e32 v52, v52, v53
	v_add_f32_e32 v52, v56, v52
	v_cvt_pk_bf16_f32 v48, v48, v49
	v_cvt_pk_bf16_f32 v49, v50, v51
	global_store_dwordx2 v[66:67], v[48:49], off offset:288
	ds_bpermute_b32 v48, v155, v52
	s_waitcnt lgkmcnt(0)
	v_add_f32_e32 v48, v52, v48
	ds_bpermute_b32 v49, v154, v48
	s_and_saveexec_b64 s[20:21], s[8:9]
	s_cbranch_execz .LBB0_1093
; __device__ __forceinline__ unsigned cvt_pk_bf16(float lo, float hi) { return ::cvtpk(lo, hi); }
;     __device__ __forceinline__ void operator()(const f32x4 (&acc)[2][2][4][2], const Unit& u, int wr, int wc, int fr, int fq, int) const {
;         const int row0 = u.pm * BM + wr * 64 + fr, col0 = u.pn * BM + wc * 32 + 4 * fq;
; #pragma unroll
;         for (int ai = 0; ai < 2; ++ai)
; #pragma unroll
;             for (int m = 0; m < 4; ++m) { const int row = row0 + ai * HALF + m * 16; const size_t off = (size_t)row * 2048 + col0; float s = 0.f;
; #pragma unroll
;                 for (int bj = 0; bj < 2; ++bj)
; #pragma unroll
;                     for (int n = 0; n < 2; ++n) { const size_t o2 = off + bj * HALF + n * 16; f32x4 bs;
;                         if (MODE == 0) bs = __builtin_nontemporal_load((const f32x4*)(base + o2));
;                         else { const u32x2 b2 = *(const u32x2*)(xb + o2); bs[0] = __builtin_bit_cast(float, b2.x << 16); bs[1] = __builtin_bit_cast(float, b2.x & 0xffff0000u); bs[2] = __builtin_bit_cast(float, b2.y << 16); bs[3] = __builtin_bit_cast(float, b2.y & 0xffff0000u); }
;                         const f32x4 o = bs + acc[ai][bj][m][n];
;                         if (MODE == 2) __builtin_nontemporal_store(o, (f32x4*)(out + o2));
;                         else { s += (o[0] * o[0] + o[1] * o[1]) + (o[2] * o[2] + o[3] * o[3]); u32x2 w; w.x = cvt_pk_bf16(o[0], o[1]); w.y = cvt_pk_bf16(o[2], o[3]); *(u32x2*)(xb + o2) = w; } }
;                 if (MODE != 2) { s += __shfl_xor(s, 16); s += __shfl_xor(s, 32); if (fq == 0) ssq[(size_t)row * 32 + u.pn * 4 + wc] = s; } }
	v_readlane_b32 s22, v237, 48
	s_waitcnt lgkmcnt(0)
	v_add_f32_e32 v50, v48, v49
	v_lshlrev_b64 v[48:49], 7, v[64:65]
	v_readlane_b32 s23, v237, 49
	s_lshl_b32 s0, s34, 2
	s_nop 0
	v_lshl_add_u64 v[48:49], s[22:23], 0, v[48:49]
	v_lshl_add_u64 v[48:49], s[18:19], 2, v[48:49]
	v_lshl_add_u64 v[48:49], v[48:49], 0, s[0:1]
	global_store_dword v[48:49], v50, off
.LBB0_1093:
	s_or_b64 exec, exec, s[20:21]
	v_add_u32_e32 v48, 0x90, v144
	s_waitcnt lgkmcnt(0)
	v_ashrrev_i32_e32 v49, 31, v48
	v_lshlrev_b64 v[50:51], 12, v[48:49]
	v_lshl_add_u64 v[50:51], s[80:81], 0, v[50:51]
	v_lshl_add_u64 v[50:51], v[142:143], 1, v[50:51]
	s_waitcnt vmcnt(11)
	s_nop 1
	v_mov_b32_e32 v52, v164
	v_mov_b32_e32 v53, v165
	global_load_dwordx2 v[164:165], v180, s[80:81] offset:256
	v_lshlrev_b32_e32 v54, 16, v52
	v_and_b32_e32 v55, 0xffff0000, v52
	v_lshlrev_b32_e32 v52, 16, v53
	v_and_b32_e32 v53, 0xffff0000, v53
	v_pk_add_f32 v[44:45], v[44:45], v[54:55]
	v_pk_add_f32 v[46:47], v[46:47], v[52:53]
	v_mul_f32_e32 v52, v45, v45
	v_fmac_f32_e32 v52, v44, v44
	v_cvt_pk_bf16_f32 v44, v44, v45
	v_cvt_pk_bf16_f32 v45, v46, v47
	global_store_dwordx2 v[50:51], v[44:45], off
	s_waitcnt vmcnt(11)
	s_nop 1
	v_mov_b32_e32 v44, v166
	v_mov_b32_e32 v45, v167
	global_load_dwordx2 v[166:167], v180, s[80:81] offset:288
	v_mul_f32_e32 v53, v47, v47
	v_fmac_f32_e32 v53, v46, v46
	v_add_f32_e32 v52, v52, v53
	v_lshlrev_b32_e32 v46, 16, v44
	v_and_b32_e32 v47, 0xffff0000, v44
	v_lshlrev_b32_e32 v44, 16, v45
	v_and_b32_e32 v45, 0xffff0000, v45
	v_pk_add_f32 v[40:41], v[40:41], v[46:47]
	v_pk_add_f32 v[42:43], v[42:43], v[44:45]
	v_mul_f32_e32 v44, v41, v41
	v_fmac_f32_e32 v44, v40, v40
	v_cvt_pk_bf16_f32 v40, v40, v41
	v_cvt_pk_bf16_f32 v41, v42, v43
	global_store_dwordx2 v[50:51], v[40:41], off offset:32
	s_waitcnt vmcnt(11)
	s_nop 1
	v_mov_b32_e32 v40, v168
	v_mov_b32_e32 v41, v169
	v_add_u32_e32 v180, 0xb0000, v179
	global_load_dwordx2 v[168:169], v180, s[80:81]
	v_mul_f32_e32 v45, v43, v43
	v_fmac_f32_e32 v45, v42, v42
	v_add_f32_e32 v44, v44, v45
	v_add_f32_e32 v44, v52, v44
	v_lshlrev_b32_e32 v42, 16, v40
	v_and_b32_e32 v43, 0xffff0000, v40
	v_lshlrev_b32_e32 v40, 16, v41
	v_and_b32_e32 v41, 0xffff0000, v41
	v_pk_add_f32 v[36:37], v[36:37], v[42:43]
	v_pk_add_f32 v[38:39], v[38:39], v[40:41]
	v_mul_f32_e32 v40, v37, v37
	v_fmac_f32_e32 v40, v36, v36
	v_cvt_pk_bf16_f32 v36, v36, v37
	v_cvt_pk_bf16_f32 v37, v38, v39
	global_store_dwordx2 v[50:51], v[36:37], off offset:256
	s_waitcnt vmcnt(11)
	s_nop 1
	v_mov_b32_e32 v36, v170
	v_mov_b32_e32 v37, v171
	global_load_dwordx2 v[170:171], v180, s[80:81] offset:32
	v_mul_f32_e32 v41, v39, v39
	v_fmac_f32_e32 v41, v38, v38
	v_add_f32_e32 v40, v40, v41
	v_add_f32_e32 v40, v44, v40
	v_lshlrev_b32_e32 v38, 16, v36
	v_and_b32_e32 v39, 0xffff0000, v36
	v_lshlrev_b32_e32 v36, 16, v37
	v_and_b32_e32 v37, 0xffff0000, v37
	v_pk_add_f32 v[34:35], v[34:35], v[36:37]
	v_pk_add_f32 v[32:33], v[32:33], v[38:39]
	v_mul_f32_e32 v37, v35, v35
	v_mul_f32_e32 v36, v33, v33
	v_fmac_f32_e32 v36, v32, v32
	v_fmac_f32_e32 v37, v34, v34
	v_add_f32_e32 v36, v36, v37
	v_add_f32_e32 v36, v40, v36
	v_cvt_pk_bf16_f32 v32, v32, v33
	v_cvt_pk_bf16_f32 v33, v34, v35
	global_store_dwordx2 v[50:51], v[32:33], off offset:288
	ds_bpermute_b32 v32, v155, v36
	s_waitcnt lgkmcnt(0)
	v_add_f32_e32 v32, v36, v32
	ds_bpermute_b32 v33, v154, v32
	s_and_saveexec_b64 s[20:21], s[8:9]
	s_cbranch_execz .LBB0_1095
	v_readlane_b32 s22, v237, 48
	s_waitcnt lgkmcnt(0)
	v_add_f32_e32 v34, v32, v33
	v_lshlrev_b64 v[32:33], 7, v[48:49]
	v_readlane_b32 s23, v237, 49
	s_lshl_b32 s0, s34, 2
	s_nop 0
	v_lshl_add_u64 v[32:33], s[22:23], 0, v[32:33]
	v_lshl_add_u64 v[32:33], s[18:19], 2, v[32:33]
	v_lshl_add_u64 v[32:33], v[32:33], 0, s[0:1]
	global_store_dword v[32:33], v34, off
; __device__ __forceinline__ unsigned cvt_pk_bf16(float lo, float hi) { return ::cvtpk(lo, hi); }
;     __device__ __forceinline__ void operator()(const f32x4 (&acc)[2][2][4][2], const Unit& u, int wr, int wc, int fr, int fq, int) const {
;         const int row0 = u.pm * BM + wr * 64 + fr, col0 = u.pn * BM + wc * 32 + 4 * fq;
; #pragma unroll
;         for (int ai = 0; ai < 2; ++ai)
; #pragma unroll
;             for (int m = 0; m < 4; ++m) { const int row = row0 + ai * HALF + m * 16; const size_t off = (size_t)row * 2048 + col0; float s = 0.f;
; #pragma unroll
;                 for (int bj = 0; bj < 2; ++bj)
; #pragma unroll
;                     for (int n = 0; n < 2; ++n) { const size_t o2 = off + bj * HALF + n * 16; f32x4 bs;
;                         if (MODE == 0) bs = __builtin_nontemporal_load((const f32x4*)(base + o2));
;                         else { const u32x2 b2 = *(const u32x2*)(xb + o2); bs[0] = __builtin_bit_cast(float, b2.x << 16); bs[1] = __builtin_bit_cast(float, b2.x & 0xffff0000u); bs[2] = __builtin_bit_cast(float, b2.y << 16); bs[3] = __builtin_bit_cast(float, b2.y & 0xffff0000u); }
;                         const f32x4 o = bs + acc[ai][bj][m][n];
;                         if (MODE == 2) __builtin_nontemporal_store(o, (f32x4*)(out + o2));
;                         else { s += (o[0] * o[0] + o[1] * o[1]) + (o[2] * o[2] + o[3] * o[3]); u32x2 w; w.x = cvt_pk_bf16(o[0], o[1]); w.y = cvt_pk_bf16(o[2], o[3]); *(u32x2*)(xb + o2) = w; } }
;                 if (MODE != 2) { s += __shfl_xor(s, 16); s += __shfl_xor(s, 32); if (fq == 0) ssq[(size_t)row * 32 + u.pn * 4 + wc] = s; } }
.LBB0_1095:
	s_or_b64 exec, exec, s[20:21]
	v_add_u32_e32 v32, 0xa0, v144
	s_waitcnt lgkmcnt(0)
	v_ashrrev_i32_e32 v33, 31, v32
	v_lshlrev_b64 v[34:35], 12, v[32:33]
	v_lshl_add_u64 v[34:35], s[80:81], 0, v[34:35]
	v_lshl_add_u64 v[34:35], v[142:143], 1, v[34:35]
	s_waitcnt vmcnt(11)
	s_nop 1
	v_mov_b32_e32 v36, v160
	v_mov_b32_e32 v37, v161
	global_load_dwordx2 v[160:161], v180, s[80:81] offset:256
	v_lshlrev_b32_e32 v38, 16, v36
	v_and_b32_e32 v39, 0xffff0000, v36
	v_lshlrev_b32_e32 v36, 16, v37
	v_and_b32_e32 v37, 0xffff0000, v37
	v_pk_add_f32 v[28:29], v[28:29], v[38:39]
	v_pk_add_f32 v[30:31], v[30:31], v[36:37]
	v_mul_f32_e32 v36, v29, v29
	v_fmac_f32_e32 v36, v28, v28
	v_cvt_pk_bf16_f32 v28, v28, v29
	v_cvt_pk_bf16_f32 v29, v30, v31
	global_store_dwordx2 v[34:35], v[28:29], off
	s_waitcnt vmcnt(11)
	s_nop 1
	v_mov_b32_e32 v28, v162
	v_mov_b32_e32 v29, v163
	global_load_dwordx2 v[162:163], v180, s[80:81] offset:288
	v_mul_f32_e32 v37, v31, v31
	v_fmac_f32_e32 v37, v30, v30
	v_add_f32_e32 v36, v36, v37
	v_lshlrev_b32_e32 v30, 16, v28
	v_and_b32_e32 v31, 0xffff0000, v28
	v_lshlrev_b32_e32 v28, 16, v29
	v_and_b32_e32 v29, 0xffff0000, v29
	v_pk_add_f32 v[24:25], v[24:25], v[30:31]
	v_pk_add_f32 v[26:27], v[26:27], v[28:29]
	v_mul_f32_e32 v28, v25, v25
	v_fmac_f32_e32 v28, v24, v24
	v_cvt_pk_bf16_f32 v24, v24, v25
	v_cvt_pk_bf16_f32 v25, v26, v27
	global_store_dwordx2 v[34:35], v[24:25], off offset:32
	s_waitcnt vmcnt(11)
	s_nop 1
	v_mov_b32_e32 v24, v164
	v_mov_b32_e32 v25, v165
	v_mul_f32_e32 v29, v27, v27
	v_fmac_f32_e32 v29, v26, v26
	v_add_f32_e32 v28, v28, v29
	v_add_f32_e32 v28, v36, v28
	v_lshlrev_b32_e32 v26, 16, v24
	v_and_b32_e32 v27, 0xffff0000, v24
	v_lshlrev_b32_e32 v24, 16, v25
	v_and_b32_e32 v25, 0xffff0000, v25
	v_pk_add_f32 v[20:21], v[20:21], v[26:27]
	v_pk_add_f32 v[22:23], v[22:23], v[24:25]
	v_mul_f32_e32 v24, v21, v21
	v_fmac_f32_e32 v24, v20, v20
	v_cvt_pk_bf16_f32 v20, v20, v21
	v_cvt_pk_bf16_f32 v21, v22, v23
	global_store_dwordx2 v[34:35], v[20:21], off offset:256
	s_waitcnt vmcnt(10)
	s_nop 1
	v_mov_b32_e32 v20, v166
	v_mov_b32_e32 v21, v167
	v_mul_f32_e32 v25, v23, v23
	v_fmac_f32_e32 v25, v22, v22
	v_add_f32_e32 v24, v24, v25
	v_add_f32_e32 v24, v28, v24
	v_lshlrev_b32_e32 v22, 16, v20
	v_and_b32_e32 v23, 0xffff0000, v20
	v_lshlrev_b32_e32 v20, 16, v21
	v_and_b32_e32 v21, 0xffff0000, v21
	v_pk_add_f32 v[18:19], v[18:19], v[20:21]
	v_pk_add_f32 v[16:17], v[16:17], v[22:23]
	v_mul_f32_e32 v21, v19, v19
	v_mul_f32_e32 v20, v17, v17
	v_fmac_f32_e32 v20, v16, v16
	v_fmac_f32_e32 v21, v18, v18
	v_add_f32_e32 v20, v20, v21
	v_add_f32_e32 v20, v24, v20
	v_cvt_pk_bf16_f32 v16, v16, v17
	v_cvt_pk_bf16_f32 v17, v18, v19
	global_store_dwordx2 v[34:35], v[16:17], off offset:288
	ds_bpermute_b32 v16, v155, v20
	s_waitcnt lgkmcnt(0)
	v_add_f32_e32 v16, v20, v16
	ds_bpermute_b32 v17, v154, v16
	s_and_saveexec_b64 s[20:21], s[8:9]
	s_cbranch_execz .LBB0_1097
	v_readlane_b32 s22, v237, 48
	s_waitcnt lgkmcnt(0)
	v_add_f32_e32 v18, v16, v17
	v_lshlrev_b64 v[16:17], 7, v[32:33]
	v_readlane_b32 s23, v237, 49
	s_lshl_b32 s0, s34, 2
	s_nop 0
	v_lshl_add_u64 v[16:17], s[22:23], 0, v[16:17]
	v_lshl_add_u64 v[16:17], s[18:19], 2, v[16:17]
	v_lshl_add_u64 v[16:17], v[16:17], 0, s[0:1]
	global_store_dword v[16:17], v18, off
.LBB0_1097:
	s_or_b64 exec, exec, s[20:21]
	v_add_u32_e32 v16, 0xb0, v144
	s_waitcnt lgkmcnt(0)
	v_ashrrev_i32_e32 v17, 31, v16
	v_lshlrev_b64 v[18:19], 12, v[16:17]
	v_lshl_add_u64 v[18:19], s[80:81], 0, v[18:19]
	v_lshl_add_u64 v[18:19], v[142:143], 1, v[18:19]
	s_waitcnt vmcnt(9)
	s_nop 1
	v_mov_b32_e32 v20, v168
	v_mov_b32_e32 v21, v169
	v_lshlrev_b32_e32 v22, 16, v20
	v_and_b32_e32 v23, 0xffff0000, v20
	v_lshlrev_b32_e32 v20, 16, v21
	v_and_b32_e32 v21, 0xffff0000, v21
	v_pk_add_f32 v[12:13], v[12:13], v[22:23]
	v_pk_add_f32 v[14:15], v[14:15], v[20:21]
	v_mul_f32_e32 v20, v13, v13
	v_fmac_f32_e32 v20, v12, v12
	v_cvt_pk_bf16_f32 v12, v12, v13
	v_cvt_pk_bf16_f32 v13, v14, v15
	global_store_dwordx2 v[18:19], v[12:13], off
	s_waitcnt vmcnt(8)
	s_nop 1
	v_mov_b32_e32 v12, v170
	v_mov_b32_e32 v13, v171
	v_mul_f32_e32 v21, v15, v15
	v_fmac_f32_e32 v21, v14, v14
	v_add_f32_e32 v20, v20, v21
	v_lshlrev_b32_e32 v14, 16, v12
	v_and_b32_e32 v15, 0xffff0000, v12
	v_lshlrev_b32_e32 v12, 16, v13
	v_and_b32_e32 v13, 0xffff0000, v13
	v_pk_add_f32 v[8:9], v[8:9], v[14:15]
	v_pk_add_f32 v[10:11], v[10:11], v[12:13]
	v_mul_f32_e32 v12, v9, v9
	v_fmac_f32_e32 v12, v8, v8
	v_cvt_pk_bf16_f32 v8, v8, v9
	v_cvt_pk_bf16_f32 v9, v10, v11
	global_store_dwordx2 v[18:19], v[8:9], off offset:32
	s_waitcnt vmcnt(7)
	s_nop 1
	v_mov_b32_e32 v8, v160
	v_mov_b32_e32 v9, v161
	v_mul_f32_e32 v13, v11, v11
	v_fmac_f32_e32 v13, v10, v10
	v_add_f32_e32 v12, v12, v13
	v_add_f32_e32 v12, v20, v12
	v_lshlrev_b32_e32 v10, 16, v8
	v_and_b32_e32 v11, 0xffff0000, v8
	v_lshlrev_b32_e32 v8, 16, v9
	v_and_b32_e32 v9, 0xffff0000, v9
	v_pk_add_f32 v[4:5], v[4:5], v[10:11]
	v_pk_add_f32 v[6:7], v[6:7], v[8:9]
	v_mul_f32_e32 v8, v5, v5
	v_fmac_f32_e32 v8, v4, v4
	v_cvt_pk_bf16_f32 v4, v4, v5
	v_cvt_pk_bf16_f32 v5, v6, v7
	global_store_dwordx2 v[18:19], v[4:5], off offset:256
	s_waitcnt vmcnt(6)
	s_nop 1
	v_mov_b32_e32 v4, v162
	v_mov_b32_e32 v5, v163
	v_mul_f32_e32 v9, v7, v7
	v_fmac_f32_e32 v9, v6, v6
	v_add_f32_e32 v8, v8, v9
	v_add_f32_e32 v8, v12, v8
	v_lshlrev_b32_e32 v6, 16, v4
	v_and_b32_e32 v7, 0xffff0000, v4
	v_lshlrev_b32_e32 v4, 16, v5
	v_and_b32_e32 v5, 0xffff0000, v5
	v_pk_add_f32 v[2:3], v[2:3], v[4:5]
	v_pk_add_f32 v[0:1], v[0:1], v[6:7]
	v_mul_f32_e32 v5, v3, v3
	v_mul_f32_e32 v4, v1, v1
	v_fmac_f32_e32 v4, v0, v0
	v_fmac_f32_e32 v5, v2, v2
	v_add_f32_e32 v4, v4, v5
	v_add_f32_e32 v4, v8, v4
	v_cvt_pk_bf16_f32 v0, v0, v1
	v_cvt_pk_bf16_f32 v1, v2, v3
	global_store_dwordx2 v[18:19], v[0:1], off offset:288
	ds_bpermute_b32 v0, v155, v4
	s_waitcnt lgkmcnt(0)
	v_add_f32_e32 v0, v4, v0
	ds_bpermute_b32 v1, v154, v0
	s_and_saveexec_b64 s[20:21], s[8:9]
	s_cbranch_execz .LBB0_1099
	v_readlane_b32 s22, v237, 48
	s_waitcnt lgkmcnt(0)
	v_add_f32_e32 v2, v0, v1
	v_lshlrev_b64 v[0:1], 7, v[16:17]
	v_readlane_b32 s23, v237, 49
	s_lshl_b32 s0, s34, 2
	s_nop 0
	v_lshl_add_u64 v[0:1], s[22:23], 0, v[0:1]
	v_lshl_add_u64 v[0:1], s[18:19], 2, v[0:1]
	v_lshl_add_u64 v[0:1], v[0:1], 0, s[0:1]
	global_store_dword v[0:1], v2, off

; __device__ __forceinline__ unsigned cvt_pk_bf16(float lo, float hi) { return ::cvtpk(lo, hi); }
;     __device__ __forceinline__ void operator()(const f32x4 (&acc)[2][2][4][2], const Unit& u, int wr, int wc, int fr, int fq, int) const {
;         const int row0 = u.pm * BM + wr * 64 + fr, col0 = u.pn * BM + wc * 32 + 4 * fq;
; #pragma unroll
;         for (int ai = 0; ai < 2; ++ai)
; #pragma unroll
;             for (int m = 0; m < 4; ++m) { const int row = row0 + ai * HALF + m * 16; const size_t off = (size_t)row * 2048 + col0; float s = 0.f;
; #pragma unroll
;                 for (int bj = 0; bj < 2; ++bj)
; #pragma unroll
;                     for (int n = 0; n < 2; ++n) { const size_t o2 = off + bj * HALF + n * 16; f32x4 bs;
;                         if (MODE == 0) bs = __builtin_nontemporal_load((const f32x4*)(base + o2));
;                         else { const u32x2 b2 = *(const u32x2*)(xb + o2); bs[0] = __builtin_bit_cast(float, b2.x << 16); bs[1] = __builtin_bit_cast(float, b2.x & 0xffff0000u); bs[2] = __builtin_bit_cast(float, b2.y << 16); bs[3] = __builtin_bit_cast(float, b2.y & 0xffff0000u); }
;                         const f32x4 o = bs + acc[ai][bj][m][n];
;                         if (MODE == 2) __builtin_nontemporal_store(o, (f32x4*)(out + o2));
;                         else { s += (o[0] * o[0] + o[1] * o[1]) + (o[2] * o[2] + o[3] * o[3]); u32x2 w; w.x = cvt_pk_bf16(o[0], o[1]); w.y = cvt_pk_bf16(o[2], o[3]); *(u32x2*)(xb + o2) = w; } }
;                 if (MODE != 2) { s += __shfl_xor(s, 16); s += __shfl_xor(s, 32); if (fq == 0) ssq[(size_t)row * 32 + u.pn * 4 + wc] = s; } }
.LBB0_1460:
	v_xor_b32_e32 v145, 16, v175
	v_cmp_lt_i32_e32 vcc, v145, v177
	v_lshl_add_u32 v144, s20, 8, v148
	v_lshl_or_b32 v142, s0, 8, v150
	v_cndmask_b32_e32 v145, v175, v145, vcc
	v_lshlrev_b32_e32 v155, 2, v145
	v_xor_b32_e32 v145, 32, v175
	v_cmp_lt_i32_e32 vcc, v145, v177
	v_ashrrev_i32_e32 v143, 31, v142
	s_lshl_b32 s20, s0, 2
	v_cndmask_b32_e32 v145, v175, v145, vcc
	v_lshlrev_b32_e32 v154, 2, v145
	v_ashrrev_i32_e32 v145, 31, v144
	v_lshlrev_b64 v[146:147], 12, v[144:145]
	v_lshl_add_u64 v[146:147], s[80:81], 0, v[146:147]
	v_lshl_add_u64 v[146:147], v[142:143], 1, v[146:147]
	s_nop 4
	v_subrev_u32_e32 v178, s80, v146
	s_nop 1
	global_load_dwordx2 v[160:161], v178, s[80:81]
	global_load_dwordx2 v[162:163], v178, s[80:81] offset:32
	global_load_dwordx2 v[164:165], v178, s[80:81] offset:256
	global_load_dwordx2 v[166:167], v178, s[80:81] offset:288
	v_add_u32_e32 v179, 0x10000, v178
	global_load_dwordx2 v[168:169], v179, s[80:81]
	global_load_dwordx2 v[170:171], v179, s[80:81] offset:32
	s_waitcnt vmcnt(5)
	s_nop 1
	v_mov_b32_e32 v156, v160
	v_mov_b32_e32 v157, v161
	global_load_dwordx2 v[160:161], v179, s[80:81] offset:256
	s_ashr_i32 s21, s20, 31
	v_lshlrev_b32_e32 v158, 16, v156
	v_and_b32_e32 v159, 0xffff0000, v156
	v_lshlrev_b32_e32 v156, 16, v157
	v_and_b32_e32 v157, 0xffff0000, v157
	v_pk_add_f32 v[124:125], v[124:125], v[158:159]
	v_pk_add_f32 v[126:127], v[126:127], v[156:157]
	v_mul_f32_e32 v156, v125, v125
	v_fmac_f32_e32 v156, v124, v124
	v_cvt_pk_bf16_f32 v124, v124, v125
	v_cvt_pk_bf16_f32 v125, v126, v127
	global_store_dwordx2 v[146:147], v[124:125], off
	s_waitcnt vmcnt(6)
	s_nop 1
	v_mov_b32_e32 v124, v162
	v_mov_b32_e32 v125, v163
	global_load_dwordx2 v[162:163], v179, s[80:81] offset:288
	v_mul_f32_e32 v157, v127, v127
	v_fmac_f32_e32 v157, v126, v126
	v_add_f32_e32 v156, v156, v157
	v_lshlrev_b32_e32 v126, 16, v124
	v_and_b32_e32 v127, 0xffff0000, v124
	v_lshlrev_b32_e32 v124, 16, v125
	v_and_b32_e32 v125, 0xffff0000, v125
	v_pk_add_f32 v[120:121], v[120:121], v[126:127]
	v_pk_add_f32 v[122:123], v[122:123], v[124:125]
	v_mul_f32_e32 v124, v121, v121
	v_fmac_f32_e32 v124, v120, v120
	v_cvt_pk_bf16_f32 v120, v120, v121
	v_cvt_pk_bf16_f32 v121, v122, v123
	global_store_dwordx2 v[146:147], v[120:121], off offset:32
	s_waitcnt vmcnt(7)
	s_nop 1
	v_mov_b32_e32 v120, v164
	v_mov_b32_e32 v121, v165
	v_add_u32_e32 v179, 0x20000, v178
	global_load_dwordx2 v[164:165], v179, s[80:81]
	v_mul_f32_e32 v125, v123, v123
	v_fmac_f32_e32 v125, v122, v122
	v_add_f32_e32 v124, v124, v125
	v_add_f32_e32 v124, v156, v124
	v_lshlrev_b32_e32 v122, 16, v120
	v_and_b32_e32 v123, 0xffff0000, v120
	v_lshlrev_b32_e32 v120, 16, v121
	v_and_b32_e32 v121, 0xffff0000, v121
	v_pk_add_f32 v[116:117], v[116:117], v[122:123]
	v_pk_add_f32 v[118:119], v[118:119], v[120:121]
	v_mul_f32_e32 v120, v117, v117
	v_fmac_f32_e32 v120, v116, v116
	v_cvt_pk_bf16_f32 v116, v116, v117
	v_cvt_pk_bf16_f32 v117, v118, v119
	global_store_dwordx2 v[146:147], v[116:117], off offset:256
	s_waitcnt vmcnt(8)
	s_nop 1
	v_mov_b32_e32 v116, v166
	v_mov_b32_e32 v117, v167
	global_load_dwordx2 v[166:167], v179, s[80:81] offset:32
	v_mul_f32_e32 v121, v119, v119
	v_fmac_f32_e32 v121, v118, v118
	v_add_f32_e32 v120, v120, v121
	v_add_f32_e32 v120, v124, v120
	v_lshlrev_b32_e32 v118, 16, v116
	v_and_b32_e32 v119, 0xffff0000, v116
	v_lshlrev_b32_e32 v116, 16, v117
	v_and_b32_e32 v117, 0xffff0000, v117
	v_pk_add_f32 v[114:115], v[114:115], v[116:117]
	v_pk_add_f32 v[112:113], v[112:113], v[118:119]
	v_mul_f32_e32 v117, v115, v115
	v_mul_f32_e32 v116, v113, v113
	v_fmac_f32_e32 v116, v112, v112
	v_fmac_f32_e32 v117, v114, v114
	v_add_f32_e32 v116, v116, v117
	v_add_f32_e32 v116, v120, v116
	v_cvt_pk_bf16_f32 v112, v112, v113
	v_cvt_pk_bf16_f32 v113, v114, v115
	global_store_dwordx2 v[146:147], v[112:113], off offset:288
	ds_bpermute_b32 v112, v155, v116
	s_waitcnt lgkmcnt(0)
	v_add_f32_e32 v112, v116, v112
	ds_bpermute_b32 v113, v154, v112
	s_and_saveexec_b64 s[22:23], s[8:9]
	s_cbranch_execz .LBB0_1462
	v_readlane_b32 s24, v237, 48
	s_waitcnt lgkmcnt(0)
	v_add_f32_e32 v114, v112, v113
	v_lshlrev_b64 v[112:113], 7, v[144:145]
	v_readlane_b32 s25, v237, 49
	s_lshl_b32 s0, s38, 2
	s_nop 0
	v_lshl_add_u64 v[112:113], s[24:25], 0, v[112:113]
	v_lshl_add_u64 v[112:113], s[20:21], 2, v[112:113]
	v_lshl_add_u64 v[112:113], v[112:113], 0, s[0:1]
	global_store_dword v[112:113], v114, off
; __device__ __forceinline__ unsigned cvt_pk_bf16(float lo, float hi) { return ::cvtpk(lo, hi); }
;     __device__ __forceinline__ void operator()(const f32x4 (&acc)[2][2][4][2], const Unit& u, int wr, int wc, int fr, int fq, int) const {
;         const int row0 = u.pm * BM + wr * 64 + fr, col0 = u.pn * BM + wc * 32 + 4 * fq;
; #pragma unroll
;         for (int ai = 0; ai < 2; ++ai)
; #pragma unroll
;             for (int m = 0; m < 4; ++m) { const int row = row0 + ai * HALF + m * 16; const size_t off = (size_t)row * 2048 + col0; float s = 0.f;
; #pragma unroll
;                 for (int bj = 0; bj < 2; ++bj)
; #pragma unroll
;                     for (int n = 0; n < 2; ++n) { const size_t o2 = off + bj * HALF + n * 16; f32x4 bs;
;                         if (MODE == 0) bs = __builtin_nontemporal_load((const f32x4*)(base + o2));
;                         else { const u32x2 b2 = *(const u32x2*)(xb + o2); bs[0] = __builtin_bit_cast(float, b2.x << 16); bs[1] = __builtin_bit_cast(float, b2.x & 0xffff0000u); bs[2] = __builtin_bit_cast(float, b2.y << 16); bs[3] = __builtin_bit_cast(float, b2.y & 0xffff0000u); }
;                         const f32x4 o = bs + acc[ai][bj][m][n];
;                         if (MODE == 2) __builtin_nontemporal_store(o, (f32x4*)(out + o2));
;                         else { s += (o[0] * o[0] + o[1] * o[1]) + (o[2] * o[2] + o[3] * o[3]); u32x2 w; w.x = cvt_pk_bf16(o[0], o[1]); w.y = cvt_pk_bf16(o[2], o[3]); *(u32x2*)(xb + o2) = w; } }
;                 if (MODE != 2) { s += __shfl_xor(s, 16); s += __shfl_xor(s, 32); if (fq == 0) ssq[(size_t)row * 32 + u.pn * 4 + wc] = s; } }
.LBB0_1462:
	s_or_b64 exec, exec, s[22:23]
	v_or_b32_e32 v112, 16, v144
	s_waitcnt lgkmcnt(0)
	v_ashrrev_i32_e32 v113, 31, v112
	v_lshlrev_b64 v[114:115], 12, v[112:113]
	v_lshl_add_u64 v[114:115], s[80:81], 0, v[114:115]
	v_lshl_add_u64 v[114:115], v[142:143], 1, v[114:115]
	s_waitcnt vmcnt(9)
	s_nop 1
	v_mov_b32_e32 v116, v168
	v_mov_b32_e32 v117, v169
	global_load_dwordx2 v[168:169], v179, s[80:81] offset:256
	v_lshlrev_b32_e32 v118, 16, v116
	v_and_b32_e32 v119, 0xffff0000, v116
	v_lshlrev_b32_e32 v116, 16, v117
	v_and_b32_e32 v117, 0xffff0000, v117
	v_pk_add_f32 v[108:109], v[108:109], v[118:119]
	v_pk_add_f32 v[110:111], v[110:111], v[116:117]
	v_mul_f32_e32 v116, v109, v109
	v_fmac_f32_e32 v116, v108, v108
	v_cvt_pk_bf16_f32 v108, v108, v109
	v_cvt_pk_bf16_f32 v109, v110, v111
	global_store_dwordx2 v[114:115], v[108:109], off
	s_waitcnt vmcnt(10)
	s_nop 1
	v_mov_b32_e32 v108, v170
	v_mov_b32_e32 v109, v171
	global_load_dwordx2 v[170:171], v179, s[80:81] offset:288
	v_mul_f32_e32 v117, v111, v111
	v_fmac_f32_e32 v117, v110, v110
	v_add_f32_e32 v116, v116, v117
	v_lshlrev_b32_e32 v110, 16, v108
	v_and_b32_e32 v111, 0xffff0000, v108
	v_lshlrev_b32_e32 v108, 16, v109
	v_and_b32_e32 v109, 0xffff0000, v109
	v_pk_add_f32 v[104:105], v[104:105], v[110:111]
	v_pk_add_f32 v[106:107], v[106:107], v[108:109]
	v_mul_f32_e32 v108, v105, v105
	v_fmac_f32_e32 v108, v104, v104
	v_cvt_pk_bf16_f32 v104, v104, v105
	v_cvt_pk_bf16_f32 v105, v106, v107
	global_store_dwordx2 v[114:115], v[104:105], off offset:32
	s_waitcnt vmcnt(11)
	s_nop 1
	v_mov_b32_e32 v104, v160
	v_mov_b32_e32 v105, v161
	v_add_u32_e32 v179, 0x30000, v178
	global_load_dwordx2 v[160:161], v179, s[80:81]
	v_mul_f32_e32 v109, v107, v107
	v_fmac_f32_e32 v109, v106, v106
	v_add_f32_e32 v108, v108, v109
	v_add_f32_e32 v108, v116, v108
	v_lshlrev_b32_e32 v106, 16, v104
	v_and_b32_e32 v107, 0xffff0000, v104
	v_lshlrev_b32_e32 v104, 16, v105
	v_and_b32_e32 v105, 0xffff0000, v105
	v_pk_add_f32 v[100:101], v[100:101], v[106:107]
	v_pk_add_f32 v[102:103], v[102:103], v[104:105]
	v_mul_f32_e32 v104, v101, v101
	v_fmac_f32_e32 v104, v100, v100
	v_cvt_pk_bf16_f32 v100, v100, v101
	v_cvt_pk_bf16_f32 v101, v102, v103
	global_store_dwordx2 v[114:115], v[100:101], off offset:256
	s_waitcnt vmcnt(11)
	s_nop 1
	v_mov_b32_e32 v100, v162
	v_mov_b32_e32 v101, v163
	global_load_dwordx2 v[162:163], v179, s[80:81] offset:32
	v_mul_f32_e32 v105, v103, v103
	v_fmac_f32_e32 v105, v102, v102
	v_add_f32_e32 v104, v104, v105
	v_add_f32_e32 v104, v108, v104
	v_lshlrev_b32_e32 v102, 16, v100
	v_and_b32_e32 v103, 0xffff0000, v100
	v_lshlrev_b32_e32 v100, 16, v101
	v_and_b32_e32 v101, 0xffff0000, v101
	v_pk_add_f32 v[98:99], v[98:99], v[100:101]
	v_pk_add_f32 v[96:97], v[96:97], v[102:103]
	v_mul_f32_e32 v101, v99, v99
	v_mul_f32_e32 v100, v97, v97
	v_fmac_f32_e32 v100, v96, v96
	v_fmac_f32_e32 v101, v98, v98
	v_add_f32_e32 v100, v100, v101
	v_add_f32_e32 v100, v104, v100
	v_cvt_pk_bf16_f32 v96, v96, v97
	v_cvt_pk_bf16_f32 v97, v98, v99
	global_store_dwordx2 v[114:115], v[96:97], off offset:288
	ds_bpermute_b32 v96, v155, v100
	s_waitcnt lgkmcnt(0)
	v_add_f32_e32 v96, v100, v96
	ds_bpermute_b32 v97, v154, v96
	s_and_saveexec_b64 s[22:23], s[8:9]
	s_cbranch_execz .LBB0_1464
	v_readlane_b32 s24, v237, 48
	s_waitcnt lgkmcnt(0)
	v_add_f32_e32 v98, v96, v97
	v_lshlrev_b64 v[96:97], 7, v[112:113]
	v_readlane_b32 s25, v237, 49
	s_lshl_b32 s0, s38, 2
	s_nop 0
	v_lshl_add_u64 v[96:97], s[24:25], 0, v[96:97]
	v_lshl_add_u64 v[96:97], s[20:21], 2, v[96:97]
	v_lshl_add_u64 v[96:97], v[96:97], 0, s[0:1]
	global_store_dword v[96:97], v98, off
.LBB0_1464:
	s_or_b64 exec, exec, s[22:23]
	v_or_b32_e32 v96, 32, v144
	s_waitcnt lgkmcnt(0)
	v_ashrrev_i32_e32 v97, 31, v96
	v_lshlrev_b64 v[98:99], 12, v[96:97]
	v_lshl_add_u64 v[98:99], s[80:81], 0, v[98:99]
	v_lshl_add_u64 v[98:99], v[142:143], 1, v[98:99]
	s_waitcnt vmcnt(11)
	s_nop 1
	v_mov_b32_e32 v100, v164
	v_mov_b32_e32 v101, v165
	global_load_dwordx2 v[164:165], v179, s[80:81] offset:256
	v_lshlrev_b32_e32 v102, 16, v100
	v_and_b32_e32 v103, 0xffff0000, v100
	v_lshlrev_b32_e32 v100, 16, v101
	v_and_b32_e32 v101, 0xffff0000, v101
	v_pk_add_f32 v[92:93], v[92:93], v[102:103]
	v_pk_add_f32 v[94:95], v[94:95], v[100:101]
	v_mul_f32_e32 v100, v93, v93
	v_fmac_f32_e32 v100, v92, v92
	v_cvt_pk_bf16_f32 v92, v92, v93
	v_cvt_pk_bf16_f32 v93, v94, v95
	global_store_dwordx2 v[98:99], v[92:93], off
	s_waitcnt vmcnt(11)
	s_nop 1
	v_mov_b32_e32 v92, v166
	v_mov_b32_e32 v93, v167
	global_load_dwordx2 v[166:167], v179, s[80:81] offset:288
	v_mul_f32_e32 v101, v95, v95
	v_fmac_f32_e32 v101, v94, v94
	v_add_f32_e32 v100, v100, v101
	v_lshlrev_b32_e32 v94, 16, v92
	v_and_b32_e32 v95, 0xffff0000, v92
	v_lshlrev_b32_e32 v92, 16, v93
	v_and_b32_e32 v93, 0xffff0000, v93
	v_pk_add_f32 v[88:89], v[88:89], v[94:95]
	v_pk_add_f32 v[90:91], v[90:91], v[92:93]
	v_mul_f32_e32 v92, v89, v89
	v_fmac_f32_e32 v92, v88, v88
	v_cvt_pk_bf16_f32 v88, v88, v89
	v_cvt_pk_bf16_f32 v89, v90, v91
	global_store_dwordx2 v[98:99], v[88:89], off offset:32
	s_waitcnt vmcnt(11)
	s_nop 1
	v_mov_b32_e32 v88, v168
	v_mov_b32_e32 v89, v169
	v_add_u32_e32 v179, 0x80000, v178
	global_load_dwordx2 v[168:169], v179, s[80:81]
	v_mul_f32_e32 v93, v91, v91
	v_fmac_f32_e32 v93, v90, v90
	v_add_f32_e32 v92, v92, v93
	v_add_f32_e32 v92, v100, v92
	v_lshlrev_b32_e32 v90, 16, v88
	v_and_b32_e32 v91, 0xffff0000, v88
	v_lshlrev_b32_e32 v88, 16, v89
	v_and_b32_e32 v89, 0xffff0000, v89
	v_pk_add_f32 v[84:85], v[84:85], v[90:91]
	v_pk_add_f32 v[86:87], v[86:87], v[88:89]
	v_mul_f32_e32 v88, v85, v85
	v_fmac_f32_e32 v88, v84, v84
	v_cvt_pk_bf16_f32 v84, v84, v85
	v_cvt_pk_bf16_f32 v85, v86, v87
	global_store_dwordx2 v[98:99], v[84:85], off offset:256
	s_waitcnt vmcnt(11)
	s_nop 1
	v_mov_b32_e32 v84, v170
	v_mov_b32_e32 v85, v171
	global_load_dwordx2 v[170:171], v179, s[80:81] offset:32
	v_mul_f32_e32 v89, v87, v87
	v_fmac_f32_e32 v89, v86, v86
	v_add_f32_e32 v88, v88, v89
	v_add_f32_e32 v88, v92, v88
	v_lshlrev_b32_e32 v86, 16, v84
	v_and_b32_e32 v87, 0xffff0000, v84
	v_lshlrev_b32_e32 v84, 16, v85
	v_and_b32_e32 v85, 0xffff0000, v85
	v_pk_add_f32 v[82:83], v[82:83], v[84:85]
	v_pk_add_f32 v[80:81], v[80:81], v[86:87]
	v_mul_f32_e32 v85, v83, v83
	v_mul_f32_e32 v84, v81, v81
	v_fmac_f32_e32 v84, v80, v80
	v_fmac_f32_e32 v85, v82, v82
	v_add_f32_e32 v84, v84, v85
	v_add_f32_e32 v84, v88, v84
	v_cvt_pk_bf16_f32 v80, v80, v81
	v_cvt_pk_bf16_f32 v81, v82, v83
	global_store_dwordx2 v[98:99], v[80:81], off offset:288
	ds_bpermute_b32 v80, v155, v84
	s_waitcnt lgkmcnt(0)
	v_add_f32_e32 v80, v84, v80
	ds_bpermute_b32 v81, v154, v80
	s_and_saveexec_b64 s[22:23], s[8:9]
	s_cbranch_execz .LBB0_1466
; __device__ __forceinline__ unsigned cvt_pk_bf16(float lo, float hi) { return ::cvtpk(lo, hi); }
;     __device__ __forceinline__ void operator()(const f32x4 (&acc)[2][2][4][2], const Unit& u, int wr, int wc, int fr, int fq, int) const {
;         const int row0 = u.pm * BM + wr * 64 + fr, col0 = u.pn * BM + wc * 32 + 4 * fq;
; #pragma unroll
;         for (int ai = 0; ai < 2; ++ai)
; #pragma unroll
;             for (int m = 0; m < 4; ++m) { const int row = row0 + ai * HALF + m * 16; const size_t off = (size_t)row * 2048 + col0; float s = 0.f;
; #pragma unroll
;                 for (int bj = 0; bj < 2; ++bj)
; #pragma unroll
;                     for (int n = 0; n < 2; ++n) { const size_t o2 = off + bj * HALF + n * 16; f32x4 bs;
;                         if (MODE == 0) bs = __builtin_nontemporal_load((const f32x4*)(base + o2));
;                         else { const u32x2 b2 = *(const u32x2*)(xb + o2); bs[0] = __builtin_bit_cast(float, b2.x << 16); bs[1] = __builtin_bit_cast(float, b2.x & 0xffff0000u); bs[2] = __builtin_bit_cast(float, b2.y << 16); bs[3] = __builtin_bit_cast(float, b2.y & 0xffff0000u); }
;                         const f32x4 o = bs + acc[ai][bj][m][n];
;                         if (MODE == 2) __builtin_nontemporal_store(o, (f32x4*)(out + o2));
;                         else { s += (o[0] * o[0] + o[1] * o[1]) + (o[2] * o[2] + o[3] * o[3]); u32x2 w; w.x = cvt_pk_bf16(o[0], o[1]); w.y = cvt_pk_bf16(o[2], o[3]); *(u32x2*)(xb + o2) = w; } }
;                 if (MODE != 2) { s += __shfl_xor(s, 16); s += __shfl_xor(s, 32); if (fq == 0) ssq[(size_t)row * 32 + u.pn * 4 + wc] = s; } }
	v_readlane_b32 s24, v237, 48
	s_waitcnt lgkmcnt(0)
	v_add_f32_e32 v82, v80, v81
	v_lshlrev_b64 v[80:81], 7, v[96:97]
	v_readlane_b32 s25, v237, 49
	s_lshl_b32 s0, s38, 2
	s_nop 0
	v_lshl_add_u64 v[80:81], s[24:25], 0, v[80:81]
	v_lshl_add_u64 v[80:81], s[20:21], 2, v[80:81]
	v_lshl_add_u64 v[80:81], v[80:81], 0, s[0:1]
	global_store_dword v[80:81], v82, off
.LBB0_1466:
	s_or_b64 exec, exec, s[22:23]
	v_or_b32_e32 v80, 48, v144
	s_waitcnt lgkmcnt(0)
	v_ashrrev_i32_e32 v81, 31, v80
	v_lshlrev_b64 v[82:83], 12, v[80:81]
	v_lshl_add_u64 v[82:83], s[80:81], 0, v[82:83]
	v_lshl_add_u64 v[82:83], v[142:143], 1, v[82:83]
	s_waitcnt vmcnt(11)
	s_nop 1
	v_mov_b32_e32 v84, v160
	v_mov_b32_e32 v85, v161
	global_load_dwordx2 v[160:161], v179, s[80:81] offset:256
	v_lshlrev_b32_e32 v86, 16, v84
	v_and_b32_e32 v87, 0xffff0000, v84
	v_lshlrev_b32_e32 v84, 16, v85
	v_and_b32_e32 v85, 0xffff0000, v85
	v_pk_add_f32 v[76:77], v[76:77], v[86:87]
	v_pk_add_f32 v[78:79], v[78:79], v[84:85]
	v_mul_f32_e32 v84, v77, v77
	v_fmac_f32_e32 v84, v76, v76
	v_cvt_pk_bf16_f32 v76, v76, v77
	v_cvt_pk_bf16_f32 v77, v78, v79
	global_store_dwordx2 v[82:83], v[76:77], off
	s_waitcnt vmcnt(11)
	s_nop 1
	v_mov_b32_e32 v76, v162
	v_mov_b32_e32 v77, v163
	global_load_dwordx2 v[162:163], v179, s[80:81] offset:288
	v_mul_f32_e32 v85, v79, v79
	v_fmac_f32_e32 v85, v78, v78
	v_add_f32_e32 v84, v84, v85
	v_lshlrev_b32_e32 v78, 16, v76
	v_and_b32_e32 v79, 0xffff0000, v76
	v_lshlrev_b32_e32 v76, 16, v77
	v_and_b32_e32 v77, 0xffff0000, v77
	v_pk_add_f32 v[72:73], v[72:73], v[78:79]
	v_pk_add_f32 v[74:75], v[74:75], v[76:77]
	v_mul_f32_e32 v76, v73, v73
	v_fmac_f32_e32 v76, v72, v72
	v_cvt_pk_bf16_f32 v72, v72, v73
	v_cvt_pk_bf16_f32 v73, v74, v75
	global_store_dwordx2 v[82:83], v[72:73], off offset:32
	s_waitcnt vmcnt(11)
	s_nop 1
	v_mov_b32_e32 v72, v164
	v_mov_b32_e32 v73, v165
	v_add_u32_e32 v179, 0x90000, v178
	global_load_dwordx2 v[164:165], v179, s[80:81]
	v_mul_f32_e32 v77, v75, v75
	v_fmac_f32_e32 v77, v74, v74
	v_add_f32_e32 v76, v76, v77
	v_add_f32_e32 v76, v84, v76
	v_lshlrev_b32_e32 v74, 16, v72
	v_and_b32_e32 v75, 0xffff0000, v72
	v_lshlrev_b32_e32 v72, 16, v73
	v_and_b32_e32 v73, 0xffff0000, v73
	v_pk_add_f32 v[68:69], v[68:69], v[74:75]
	v_pk_add_f32 v[70:71], v[70:71], v[72:73]
	v_mul_f32_e32 v72, v69, v69
	v_fmac_f32_e32 v72, v68, v68
	v_cvt_pk_bf16_f32 v68, v68, v69
	v_cvt_pk_bf16_f32 v69, v70, v71
	global_store_dwordx2 v[82:83], v[68:69], off offset:256
	s_waitcnt vmcnt(11)
	s_nop 1
	v_mov_b32_e32 v68, v166
	v_mov_b32_e32 v69, v167
	global_load_dwordx2 v[166:167], v179, s[80:81] offset:32
	v_mul_f32_e32 v73, v71, v71
	v_fmac_f32_e32 v73, v70, v70
	v_add_f32_e32 v72, v72, v73
	v_add_f32_e32 v72, v76, v72
	v_lshlrev_b32_e32 v70, 16, v68
	v_and_b32_e32 v71, 0xffff0000, v68
	v_lshlrev_b32_e32 v68, 16, v69
	v_and_b32_e32 v69, 0xffff0000, v69
	v_pk_add_f32 v[66:67], v[66:67], v[68:69]
	v_pk_add_f32 v[64:65], v[64:65], v[70:71]
	v_mul_f32_e32 v69, v67, v67
	v_mul_f32_e32 v68, v65, v65
	v_fmac_f32_e32 v68, v64, v64
	v_fmac_f32_e32 v69, v66, v66
	v_add_f32_e32 v68, v68, v69
	v_add_f32_e32 v68, v72, v68
	v_cvt_pk_bf16_f32 v64, v64, v65
	v_cvt_pk_bf16_f32 v65, v66, v67
	global_store_dwordx2 v[82:83], v[64:65], off offset:288
	ds_bpermute_b32 v64, v155, v68
	s_waitcnt lgkmcnt(0)
	v_add_f32_e32 v64, v68, v64
	ds_bpermute_b32 v65, v154, v64
	s_and_saveexec_b64 s[22:23], s[8:9]
	s_cbranch_execz .LBB0_1468
	v_readlane_b32 s24, v237, 48
	s_waitcnt lgkmcnt(0)
	v_add_f32_e32 v66, v64, v65
	v_lshlrev_b64 v[64:65], 7, v[80:81]
	v_readlane_b32 s25, v237, 49
	s_lshl_b32 s0, s38, 2
	s_nop 0
	v_lshl_add_u64 v[64:65], s[24:25], 0, v[64:65]
	v_lshl_add_u64 v[64:65], s[20:21], 2, v[64:65]
	v_lshl_add_u64 v[64:65], v[64:65], 0, s[0:1]
	global_store_dword v[64:65], v66, off
.LBB0_1468:
	s_or_b64 exec, exec, s[22:23]
	v_add_u32_e32 v64, 0x80, v144
	s_waitcnt lgkmcnt(0)
	v_ashrrev_i32_e32 v65, 31, v64
	v_lshlrev_b64 v[66:67], 12, v[64:65]
	v_lshl_add_u64 v[66:67], s[80:81], 0, v[66:67]
	v_lshl_add_u64 v[66:67], v[142:143], 1, v[66:67]
	s_waitcnt vmcnt(11)
	s_nop 1
	v_mov_b32_e32 v68, v168
	v_mov_b32_e32 v69, v169
	global_load_dwordx2 v[168:169], v179, s[80:81] offset:256
	v_lshlrev_b32_e32 v70, 16, v68
	v_and_b32_e32 v71, 0xffff0000, v68
	v_lshlrev_b32_e32 v68, 16, v69
	v_and_b32_e32 v69, 0xffff0000, v69
	v_pk_add_f32 v[60:61], v[60:61], v[70:71]
	v_pk_add_f32 v[62:63], v[62:63], v[68:69]
	v_mul_f32_e32 v68, v61, v61
	v_fmac_f32_e32 v68, v60, v60
	v_cvt_pk_bf16_f32 v60, v60, v61
	v_cvt_pk_bf16_f32 v61, v62, v63
	global_store_dwordx2 v[66:67], v[60:61], off
	s_waitcnt vmcnt(11)
	s_nop 1
	v_mov_b32_e32 v60, v170
	v_mov_b32_e32 v61, v171
	global_load_dwordx2 v[170:171], v179, s[80:81] offset:288
	v_mul_f32_e32 v69, v63, v63
	v_fmac_f32_e32 v69, v62, v62
	v_add_f32_e32 v68, v68, v69
	v_lshlrev_b32_e32 v62, 16, v60
	v_and_b32_e32 v63, 0xffff0000, v60
	v_lshlrev_b32_e32 v60, 16, v61
	v_and_b32_e32 v61, 0xffff0000, v61
	v_pk_add_f32 v[56:57], v[56:57], v[62:63]
	v_pk_add_f32 v[58:59], v[58:59], v[60:61]
	v_mul_f32_e32 v60, v57, v57
	v_fmac_f32_e32 v60, v56, v56
	v_cvt_pk_bf16_f32 v56, v56, v57
	v_cvt_pk_bf16_f32 v57, v58, v59
	global_store_dwordx2 v[66:67], v[56:57], off offset:32
	s_waitcnt vmcnt(11)
	s_nop 1
	v_mov_b32_e32 v56, v160
	v_mov_b32_e32 v57, v161
	v_add_u32_e32 v179, 0xa0000, v178
	global_load_dwordx2 v[160:161], v179, s[80:81]
	v_mul_f32_e32 v61, v59, v59
	v_fmac_f32_e32 v61, v58, v58
	v_add_f32_e32 v60, v60, v61
	v_add_f32_e32 v60, v68, v60
	v_lshlrev_b32_e32 v58, 16, v56
	v_and_b32_e32 v59, 0xffff0000, v56
	v_lshlrev_b32_e32 v56, 16, v57
	v_and_b32_e32 v57, 0xffff0000, v57
	v_pk_add_f32 v[52:53], v[52:53], v[58:59]
	v_pk_add_f32 v[54:55], v[54:55], v[56:57]
	v_mul_f32_e32 v56, v53, v53
	v_fmac_f32_e32 v56, v52, v52
	v_cvt_pk_bf16_f32 v52, v52, v53
	v_cvt_pk_bf16_f32 v53, v54, v55
	global_store_dwordx2 v[66:67], v[52:53], off offset:256
	s_waitcnt vmcnt(11)
	s_nop 1
	v_mov_b32_e32 v52, v162
	v_mov_b32_e32 v53, v163
	global_load_dwordx2 v[162:163], v179, s[80:81] offset:32
	v_mul_f32_e32 v57, v55, v55
	v_fmac_f32_e32 v57, v54, v54
	v_add_f32_e32 v56, v56, v57
	v_add_f32_e32 v56, v60, v56
	v_lshlrev_b32_e32 v54, 16, v52
	v_and_b32_e32 v55, 0xffff0000, v52
	v_lshlrev_b32_e32 v52, 16, v53
	v_and_b32_e32 v53, 0xffff0000, v53
	v_pk_add_f32 v[50:51], v[50:51], v[52:53]
	v_pk_add_f32 v[48:49], v[48:49], v[54:55]
	v_mul_f32_e32 v53, v51, v51
	v_mul_f32_e32 v52, v49, v49
	v_fmac_f32_e32 v52, v48, v48
	v_fmac_f32_e32 v53, v50, v50
	v_add_f32_e32 v52, v52, v53
	v_add_f32_e32 v52, v56, v52
	v_cvt_pk_bf16_f32 v48, v48, v49
	v_cvt_pk_bf16_f32 v49, v50, v51
	global_store_dwordx2 v[66:67], v[48:49], off offset:288
	ds_bpermute_b32 v48, v155, v52
	s_waitcnt lgkmcnt(0)
	v_add_f32_e32 v48, v52, v48
	ds_bpermute_b32 v49, v154, v48
	s_and_saveexec_b64 s[22:23], s[8:9]
	s_cbranch_execz .LBB0_1470
; __device__ __forceinline__ unsigned cvt_pk_bf16(float lo, float hi) { return ::cvtpk(lo, hi); }
;     __device__ __forceinline__ void operator()(const f32x4 (&acc)[2][2][4][2], const Unit& u, int wr, int wc, int fr, int fq, int) const {
;         const int row0 = u.pm * BM + wr * 64 + fr, col0 = u.pn * BM + wc * 32 + 4 * fq;
; #pragma unroll
;         for (int ai = 0; ai < 2; ++ai)
; #pragma unroll
;             for (int m = 0; m < 4; ++m) { const int row = row0 + ai * HALF + m * 16; const size_t off = (size_t)row * 2048 + col0; float s = 0.f;
; #pragma unroll
;                 for (int bj = 0; bj < 2; ++bj)
; #pragma unroll
;                     for (int n = 0; n < 2; ++n) { const size_t o2 = off + bj * HALF + n * 16; f32x4 bs;
;                         if (MODE == 0) bs = __builtin_nontemporal_load((const f32x4*)(base + o2));
;                         else { const u32x2 b2 = *(const u32x2*)(xb + o2); bs[0] = __builtin_bit_cast(float, b2.x << 16); bs[1] = __builtin_bit_cast(float, b2.x & 0xffff0000u); bs[2] = __builtin_bit_cast(float, b2.y << 16); bs[3] = __builtin_bit_cast(float, b2.y & 0xffff0000u); }
;                         const f32x4 o = bs + acc[ai][bj][m][n];
;                         if (MODE == 2) __builtin_nontemporal_store(o, (f32x4*)(out + o2));
;                         else { s += (o[0] * o[0] + o[1] * o[1]) + (o[2] * o[2] + o[3] * o[3]); u32x2 w; w.x = cvt_pk_bf16(o[0], o[1]); w.y = cvt_pk_bf16(o[2], o[3]); *(u32x2*)(xb + o2) = w; } }
;                 if (MODE != 2) { s += __shfl_xor(s, 16); s += __shfl_xor(s, 32); if (fq == 0) ssq[(size_t)row * 32 + u.pn * 4 + wc] = s; } }
	v_readlane_b32 s24, v237, 48
	s_waitcnt lgkmcnt(0)
	v_add_f32_e32 v50, v48, v49
	v_lshlrev_b64 v[48:49], 7, v[64:65]
	v_readlane_b32 s25, v237, 49
	s_lshl_b32 s0, s38, 2
	s_nop 0
	v_lshl_add_u64 v[48:49], s[24:25], 0, v[48:49]
	v_lshl_add_u64 v[48:49], s[20:21], 2, v[48:49]
	v_lshl_add_u64 v[48:49], v[48:49], 0, s[0:1]
	global_store_dword v[48:49], v50, off
.LBB0_1470:
	s_or_b64 exec, exec, s[22:23]
	v_add_u32_e32 v48, 0x90, v144
	s_waitcnt lgkmcnt(0)
	v_ashrrev_i32_e32 v49, 31, v48
	v_lshlrev_b64 v[50:51], 12, v[48:49]
	v_lshl_add_u64 v[50:51], s[80:81], 0, v[50:51]
	v_lshl_add_u64 v[50:51], v[142:143], 1, v[50:51]
	s_waitcnt vmcnt(11)
	s_nop 1
	v_mov_b32_e32 v52, v164
	v_mov_b32_e32 v53, v165
	global_load_dwordx2 v[164:165], v179, s[80:81] offset:256
	v_lshlrev_b32_e32 v54, 16, v52
	v_and_b32_e32 v55, 0xffff0000, v52
	v_lshlrev_b32_e32 v52, 16, v53
	v_and_b32_e32 v53, 0xffff0000, v53
	v_pk_add_f32 v[44:45], v[44:45], v[54:55]
	v_pk_add_f32 v[46:47], v[46:47], v[52:53]
	v_mul_f32_e32 v52, v45, v45
	v_fmac_f32_e32 v52, v44, v44
	v_cvt_pk_bf16_f32 v44, v44, v45
	v_cvt_pk_bf16_f32 v45, v46, v47
	global_store_dwordx2 v[50:51], v[44:45], off
	s_waitcnt vmcnt(11)
	s_nop 1
	v_mov_b32_e32 v44, v166
	v_mov_b32_e32 v45, v167
	global_load_dwordx2 v[166:167], v179, s[80:81] offset:288
	v_mul_f32_e32 v53, v47, v47
	v_fmac_f32_e32 v53, v46, v46
	v_add_f32_e32 v52, v52, v53
	v_lshlrev_b32_e32 v46, 16, v44
	v_and_b32_e32 v47, 0xffff0000, v44
	v_lshlrev_b32_e32 v44, 16, v45
	v_and_b32_e32 v45, 0xffff0000, v45
	v_pk_add_f32 v[40:41], v[40:41], v[46:47]
	v_pk_add_f32 v[42:43], v[42:43], v[44:45]
	v_mul_f32_e32 v44, v41, v41
	v_fmac_f32_e32 v44, v40, v40
	v_cvt_pk_bf16_f32 v40, v40, v41
	v_cvt_pk_bf16_f32 v41, v42, v43
	global_store_dwordx2 v[50:51], v[40:41], off offset:32
	s_waitcnt vmcnt(11)
	s_nop 1
	v_mov_b32_e32 v40, v168
	v_mov_b32_e32 v41, v169
	v_add_u32_e32 v179, 0xb0000, v178
	global_load_dwordx2 v[168:169], v179, s[80:81]
	v_mul_f32_e32 v45, v43, v43
	v_fmac_f32_e32 v45, v42, v42
	v_add_f32_e32 v44, v44, v45
	v_add_f32_e32 v44, v52, v44
	v_lshlrev_b32_e32 v42, 16, v40
	v_and_b32_e32 v43, 0xffff0000, v40
	v_lshlrev_b32_e32 v40, 16, v41
	v_and_b32_e32 v41, 0xffff0000, v41
	v_pk_add_f32 v[36:37], v[36:37], v[42:43]
	v_pk_add_f32 v[38:39], v[38:39], v[40:41]
	v_mul_f32_e32 v40, v37, v37
	v_fmac_f32_e32 v40, v36, v36
	v_cvt_pk_bf16_f32 v36, v36, v37
	v_cvt_pk_bf16_f32 v37, v38, v39
	global_store_dwordx2 v[50:51], v[36:37], off offset:256
	s_waitcnt vmcnt(11)
	s_nop 1
	v_mov_b32_e32 v36, v170
	v_mov_b32_e32 v37, v171
	global_load_dwordx2 v[170:171], v179, s[80:81] offset:32
	v_mul_f32_e32 v41, v39, v39
	v_fmac_f32_e32 v41, v38, v38
	v_add_f32_e32 v40, v40, v41
	v_add_f32_e32 v40, v44, v40
	v_lshlrev_b32_e32 v38, 16, v36
	v_and_b32_e32 v39, 0xffff0000, v36
	v_lshlrev_b32_e32 v36, 16, v37
	v_and_b32_e32 v37, 0xffff0000, v37
	v_pk_add_f32 v[34:35], v[34:35], v[36:37]
	v_pk_add_f32 v[32:33], v[32:33], v[38:39]
	v_mul_f32_e32 v37, v35, v35
	v_mul_f32_e32 v36, v33, v33
	v_fmac_f32_e32 v36, v32, v32
	v_fmac_f32_e32 v37, v34, v34
	v_add_f32_e32 v36, v36, v37
	v_add_f32_e32 v36, v40, v36
	v_cvt_pk_bf16_f32 v32, v32, v33
	v_cvt_pk_bf16_f32 v33, v34, v35
	global_store_dwordx2 v[50:51], v[32:33], off offset:288
	ds_bpermute_b32 v32, v155, v36
	s_waitcnt lgkmcnt(0)
	v_add_f32_e32 v32, v36, v32
	ds_bpermute_b32 v33, v154, v32
	s_and_saveexec_b64 s[22:23], s[8:9]
	s_cbranch_execz .LBB0_1472
	v_readlane_b32 s24, v237, 48
	s_waitcnt lgkmcnt(0)
	v_add_f32_e32 v34, v32, v33
	v_lshlrev_b64 v[32:33], 7, v[48:49]
	v_readlane_b32 s25, v237, 49
	s_lshl_b32 s0, s38, 2
	s_nop 0
	v_lshl_add_u64 v[32:33], s[24:25], 0, v[32:33]
	v_lshl_add_u64 v[32:33], s[20:21], 2, v[32:33]
	v_lshl_add_u64 v[32:33], v[32:33], 0, s[0:1]
	global_store_dword v[32:33], v34, off
; __device__ __forceinline__ unsigned cvt_pk_bf16(float lo, float hi) { return ::cvtpk(lo, hi); }
;     __device__ __forceinline__ void operator()(const f32x4 (&acc)[2][2][4][2], const Unit& u, int wr, int wc, int fr, int fq, int) const {
;         const int row0 = u.pm * BM + wr * 64 + fr, col0 = u.pn * BM + wc * 32 + 4 * fq;
; #pragma unroll
;         for (int ai = 0; ai < 2; ++ai)
; #pragma unroll
;             for (int m = 0; m < 4; ++m) { const int row = row0 + ai * HALF + m * 16; const size_t off = (size_t)row * 2048 + col0; float s = 0.f;
; #pragma unroll
;                 for (int bj = 0; bj < 2; ++bj)
; #pragma unroll
;                     for (int n = 0; n < 2; ++n) { const size_t o2 = off + bj * HALF + n * 16; f32x4 bs;
;                         if (MODE == 0) bs = __builtin_nontemporal_load((const f32x4*)(base + o2));
;                         else { const u32x2 b2 = *(const u32x2*)(xb + o2); bs[0] = __builtin_bit_cast(float, b2.x << 16); bs[1] = __builtin_bit_cast(float, b2.x & 0xffff0000u); bs[2] = __builtin_bit_cast(float, b2.y << 16); bs[3] = __builtin_bit_cast(float, b2.y & 0xffff0000u); }
;                         const f32x4 o = bs + acc[ai][bj][m][n];
;                         if (MODE == 2) __builtin_nontemporal_store(o, (f32x4*)(out + o2));
;                         else { s += (o[0] * o[0] + o[1] * o[1]) + (o[2] * o[2] + o[3] * o[3]); u32x2 w; w.x = cvt_pk_bf16(o[0], o[1]); w.y = cvt_pk_bf16(o[2], o[3]); *(u32x2*)(xb + o2) = w; } }
;                 if (MODE != 2) { s += __shfl_xor(s, 16); s += __shfl_xor(s, 32); if (fq == 0) ssq[(size_t)row * 32 + u.pn * 4 + wc] = s; } }
.LBB0_1472:
	s_or_b64 exec, exec, s[22:23]
	v_add_u32_e32 v32, 0xa0, v144
	s_waitcnt lgkmcnt(0)
	v_ashrrev_i32_e32 v33, 31, v32
	v_lshlrev_b64 v[34:35], 12, v[32:33]
	v_lshl_add_u64 v[34:35], s[80:81], 0, v[34:35]
	v_lshl_add_u64 v[34:35], v[142:143], 1, v[34:35]
	s_waitcnt vmcnt(11)
	s_nop 1
	v_mov_b32_e32 v36, v160
	v_mov_b32_e32 v37, v161
	global_load_dwordx2 v[160:161], v179, s[80:81] offset:256
	v_lshlrev_b32_e32 v38, 16, v36
	v_and_b32_e32 v39, 0xffff0000, v36
	v_lshlrev_b32_e32 v36, 16, v37
	v_and_b32_e32 v37, 0xffff0000, v37
	v_pk_add_f32 v[28:29], v[28:29], v[38:39]
	v_pk_add_f32 v[30:31], v[30:31], v[36:37]
	v_mul_f32_e32 v36, v29, v29
	v_fmac_f32_e32 v36, v28, v28
	v_cvt_pk_bf16_f32 v28, v28, v29
	v_cvt_pk_bf16_f32 v29, v30, v31
	global_store_dwordx2 v[34:35], v[28:29], off
	s_waitcnt vmcnt(11)
	s_nop 1
	v_mov_b32_e32 v28, v162
	v_mov_b32_e32 v29, v163
	global_load_dwordx2 v[162:163], v179, s[80:81] offset:288
	v_mul_f32_e32 v37, v31, v31
	v_fmac_f32_e32 v37, v30, v30
	v_add_f32_e32 v36, v36, v37
	v_lshlrev_b32_e32 v30, 16, v28
	v_and_b32_e32 v31, 0xffff0000, v28
	v_lshlrev_b32_e32 v28, 16, v29
	v_and_b32_e32 v29, 0xffff0000, v29
	v_pk_add_f32 v[24:25], v[24:25], v[30:31]
	v_pk_add_f32 v[26:27], v[26:27], v[28:29]
	v_mul_f32_e32 v28, v25, v25
	v_fmac_f32_e32 v28, v24, v24
	v_cvt_pk_bf16_f32 v24, v24, v25
	v_cvt_pk_bf16_f32 v25, v26, v27
	global_store_dwordx2 v[34:35], v[24:25], off offset:32
	s_waitcnt vmcnt(11)
	s_nop 1
	v_mov_b32_e32 v24, v164
	v_mov_b32_e32 v25, v165
	v_mul_f32_e32 v29, v27, v27
	v_fmac_f32_e32 v29, v26, v26
	v_add_f32_e32 v28, v28, v29
	v_add_f32_e32 v28, v36, v28
	v_lshlrev_b32_e32 v26, 16, v24
	v_and_b32_e32 v27, 0xffff0000, v24
	v_lshlrev_b32_e32 v24, 16, v25
	v_and_b32_e32 v25, 0xffff0000, v25
	v_pk_add_f32 v[20:21], v[20:21], v[26:27]
	v_pk_add_f32 v[22:23], v[22:23], v[24:25]
	v_mul_f32_e32 v24, v21, v21
	v_fmac_f32_e32 v24, v20, v20
	v_cvt_pk_bf16_f32 v20, v20, v21
	v_cvt_pk_bf16_f32 v21, v22, v23
	global_store_dwordx2 v[34:35], v[20:21], off offset:256
	s_waitcnt vmcnt(10)
	s_nop 1
	v_mov_b32_e32 v20, v166
	v_mov_b32_e32 v21, v167
	v_mul_f32_e32 v25, v23, v23
	v_fmac_f32_e32 v25, v22, v22
	v_add_f32_e32 v24, v24, v25
	v_add_f32_e32 v24, v28, v24
	v_lshlrev_b32_e32 v22, 16, v20
	v_and_b32_e32 v23, 0xffff0000, v20
	v_lshlrev_b32_e32 v20, 16, v21
	v_and_b32_e32 v21, 0xffff0000, v21
	v_pk_add_f32 v[18:19], v[18:19], v[20:21]
	v_pk_add_f32 v[16:17], v[16:17], v[22:23]
	v_mul_f32_e32 v21, v19, v19
	v_mul_f32_e32 v20, v17, v17
	v_fmac_f32_e32 v20, v16, v16
	v_fmac_f32_e32 v21, v18, v18
	v_add_f32_e32 v20, v20, v21
	v_add_f32_e32 v20, v24, v20
	v_cvt_pk_bf16_f32 v16, v16, v17
	v_cvt_pk_bf16_f32 v17, v18, v19
	global_store_dwordx2 v[34:35], v[16:17], off offset:288
	ds_bpermute_b32 v16, v155, v20
	s_waitcnt lgkmcnt(0)
	v_add_f32_e32 v16, v20, v16
	ds_bpermute_b32 v17, v154, v16
	s_and_saveexec_b64 s[22:23], s[8:9]
	s_cbranch_execz .LBB0_1474
	v_readlane_b32 s24, v237, 48
	s_waitcnt lgkmcnt(0)
	v_add_f32_e32 v18, v16, v17
	v_lshlrev_b64 v[16:17], 7, v[32:33]
	v_readlane_b32 s25, v237, 49
	s_lshl_b32 s0, s38, 2
	s_nop 0
	v_lshl_add_u64 v[16:17], s[24:25], 0, v[16:17]
	v_lshl_add_u64 v[16:17], s[20:21], 2, v[16:17]
	v_lshl_add_u64 v[16:17], v[16:17], 0, s[0:1]
	global_store_dword v[16:17], v18, off
.LBB0_1474:
	s_or_b64 exec, exec, s[22:23]
	v_add_u32_e32 v16, 0xb0, v144
	s_waitcnt lgkmcnt(0)
	v_ashrrev_i32_e32 v17, 31, v16
	v_lshlrev_b64 v[18:19], 12, v[16:17]
	v_lshl_add_u64 v[18:19], s[80:81], 0, v[18:19]
	v_lshl_add_u64 v[18:19], v[142:143], 1, v[18:19]
	s_waitcnt vmcnt(9)
	s_nop 1
	v_mov_b32_e32 v20, v168
	v_mov_b32_e32 v21, v169
	v_lshlrev_b32_e32 v22, 16, v20
	v_and_b32_e32 v23, 0xffff0000, v20
	v_lshlrev_b32_e32 v20, 16, v21
	v_and_b32_e32 v21, 0xffff0000, v21
	v_pk_add_f32 v[12:13], v[12:13], v[22:23]
	v_pk_add_f32 v[14:15], v[14:15], v[20:21]
	v_mul_f32_e32 v20, v13, v13
	v_fmac_f32_e32 v20, v12, v12
	v_cvt_pk_bf16_f32 v12, v12, v13
	v_cvt_pk_bf16_f32 v13, v14, v15
	global_store_dwordx2 v[18:19], v[12:13], off
	s_waitcnt vmcnt(8)
	s_nop 1
	v_mov_b32_e32 v12, v170
	v_mov_b32_e32 v13, v171
	v_mul_f32_e32 v21, v15, v15
	v_fmac_f32_e32 v21, v14, v14
	v_add_f32_e32 v20, v20, v21
	v_lshlrev_b32_e32 v14, 16, v12
	v_and_b32_e32 v15, 0xffff0000, v12
	v_lshlrev_b32_e32 v12, 16, v13
	v_and_b32_e32 v13, 0xffff0000, v13
	v_pk_add_f32 v[8:9], v[8:9], v[14:15]
	v_pk_add_f32 v[10:11], v[10:11], v[12:13]
	v_mul_f32_e32 v12, v9, v9
	v_fmac_f32_e32 v12, v8, v8
	v_cvt_pk_bf16_f32 v8, v8, v9
	v_cvt_pk_bf16_f32 v9, v10, v11
	global_store_dwordx2 v[18:19], v[8:9], off offset:32
	s_waitcnt vmcnt(7)
	s_nop 1
	v_mov_b32_e32 v8, v160
	v_mov_b32_e32 v9, v161
	v_mul_f32_e32 v13, v11, v11
	v_fmac_f32_e32 v13, v10, v10
	v_add_f32_e32 v12, v12, v13
	v_add_f32_e32 v12, v20, v12
	v_lshlrev_b32_e32 v10, 16, v8
	v_and_b32_e32 v11, 0xffff0000, v8
	v_lshlrev_b32_e32 v8, 16, v9
	v_and_b32_e32 v9, 0xffff0000, v9
	v_pk_add_f32 v[4:5], v[4:5], v[10:11]
	v_pk_add_f32 v[6:7], v[6:7], v[8:9]
	v_mul_f32_e32 v8, v5, v5
	v_fmac_f32_e32 v8, v4, v4
	v_cvt_pk_bf16_f32 v4, v4, v5
	v_cvt_pk_bf16_f32 v5, v6, v7
	global_store_dwordx2 v[18:19], v[4:5], off offset:256
	s_waitcnt vmcnt(6)
	s_nop 1
	v_mov_b32_e32 v4, v162
	v_mov_b32_e32 v5, v163
	v_mul_f32_e32 v9, v7, v7
	v_fmac_f32_e32 v9, v6, v6
	v_add_f32_e32 v8, v8, v9
	v_add_f32_e32 v8, v12, v8
	v_lshlrev_b32_e32 v6, 16, v4
	v_and_b32_e32 v7, 0xffff0000, v4
	v_lshlrev_b32_e32 v4, 16, v5
	v_and_b32_e32 v5, 0xffff0000, v5
	v_pk_add_f32 v[2:3], v[2:3], v[4:5]
	v_pk_add_f32 v[0:1], v[0:1], v[6:7]
	v_mul_f32_e32 v5, v3, v3
	v_mul_f32_e32 v4, v1, v1
	v_fmac_f32_e32 v4, v0, v0
	v_fmac_f32_e32 v5, v2, v2
	v_add_f32_e32 v4, v4, v5
	v_add_f32_e32 v4, v8, v4
	v_cvt_pk_bf16_f32 v0, v0, v1
	v_cvt_pk_bf16_f32 v1, v2, v3
	global_store_dwordx2 v[18:19], v[0:1], off offset:288
	ds_bpermute_b32 v0, v155, v4
	s_waitcnt lgkmcnt(0)
	v_add_f32_e32 v0, v4, v0
	ds_bpermute_b32 v1, v154, v0
	s_and_saveexec_b64 s[22:23], s[8:9]
	s_cbranch_execz .LBB0_1476
	v_readlane_b32 s24, v237, 48
	s_waitcnt lgkmcnt(0)
	v_add_f32_e32 v2, v0, v1
	v_lshlrev_b64 v[0:1], 7, v[16:17]
	v_readlane_b32 s25, v237, 49
	s_lshl_b32 s0, s38, 2
	s_nop 0
	v_lshl_add_u64 v[0:1], s[24:25], 0, v[0:1]
	v_lshl_add_u64 v[0:1], s[20:21], 2, v[0:1]
	v_lshl_add_u64 v[0:1], v[0:1], 0, s[0:1]
	global_store_dword v[0:1], v2, off

; __device__ __forceinline__ unsigned cvt_pk_bf16(float lo, float hi) { return ::cvtpk(lo, hi); }
;     __device__ __forceinline__ void operator()(const f32x4 (&acc)[2][2][4][2], const Unit& u, int wr, int wc, int fr, int fq, int) const {
;         const int row0 = u.pm * BM + wr * 64 + fr, col0 = u.pn * BM + wc * 32 + 4 * fq;
; #pragma unroll
;         for (int ai = 0; ai < 2; ++ai)
; #pragma unroll
;             for (int m = 0; m < 4; ++m) { const int row = row0 + ai * HALF + m * 16; const size_t off = (size_t)row * 2048 + col0; float s = 0.f;
; #pragma unroll
;                 for (int bj = 0; bj < 2; ++bj)
; #pragma unroll
;                     for (int n = 0; n < 2; ++n) { const size_t o2 = off + bj * HALF + n * 16; f32x4 bs;
;                         if (MODE == 0) bs = __builtin_nontemporal_load((const f32x4*)(base + o2));
;                         else { const u32x2 b2 = *(const u32x2*)(xb + o2); bs[0] = __builtin_bit_cast(float, b2.x << 16); bs[1] = __builtin_bit_cast(float, b2.x & 0xffff0000u); bs[2] = __builtin_bit_cast(float, b2.y << 16); bs[3] = __builtin_bit_cast(float, b2.y & 0xffff0000u); }
;                         const f32x4 o = bs + acc[ai][bj][m][n];
;                         if (MODE == 2) __builtin_nontemporal_store(o, (f32x4*)(out + o2));
;                         else { s += (o[0] * o[0] + o[1] * o[1]) + (o[2] * o[2] + o[3] * o[3]); u32x2 w; w.x = cvt_pk_bf16(o[0], o[1]); w.y = cvt_pk_bf16(o[2], o[3]); *(u32x2*)(xb + o2) = w; } }
.LBB0_1959:
	v_lshl_add_u32 v144, s43, 8, v146
	v_lshl_or_b32 v142, s44, 8, v148
	v_ashrrev_i32_e32 v145, 31, v144
	v_ashrrev_i32_e32 v143, 31, v142
	v_lshlrev_b64 v[140:141], 11, v[144:145]
	v_lshl_add_u64 v[140:141], v[140:141], 0, v[142:143]
	v_lshlrev_b64 v[152:153], 1, v[140:141]
	v_lshl_add_u64 v[154:155], s[80:81], 0, v[152:153]
	s_nop 4
	v_subrev_u32_e32 v174, s80, v154
	s_nop 1
	global_load_dwordx2 v[162:163], v174, s[80:81]
	global_load_dwordx2 v[164:165], v174, s[80:81] offset:32
	global_load_dwordx2 v[166:167], v174, s[80:81] offset:256
	global_load_dwordx2 v[168:169], v174, s[80:81] offset:288
	v_add_u32_e32 v175, 0x10000, v174
	global_load_dwordx2 v[170:171], v175, s[80:81]
	global_load_dwordx2 v[172:173], v175, s[80:81] offset:32
	s_waitcnt vmcnt(5)
	s_nop 1
	v_mov_b32_e32 v154, v162
	v_mov_b32_e32 v155, v163
	global_load_dwordx2 v[162:163], v175, s[80:81] offset:256
	v_lshl_add_u64 v[156:157], v[140:141], 2, s[88:89]
	v_or_b32_e32 v158, 32, v152
	v_mov_b32_e32 v159, v153
	v_lshl_add_u64 v[158:159], s[80:81], 0, v[158:159]
	s_and_b64 vcc, exec, s[0:1]
	s_mov_b64 s[0:1], -1
	v_lshlrev_b32_e32 v160, 16, v154
	v_and_b32_e32 v161, 0xffff0000, v154
	v_lshlrev_b32_e32 v154, 16, v155
	v_and_b32_e32 v155, 0xffff0000, v155
	v_pk_add_f32 v[126:127], v[126:127], v[154:155]
	v_pk_add_f32 v[124:125], v[124:125], v[160:161]
	global_store_dwordx4 v[156:157], v[124:127], off nt
	s_waitcnt vmcnt(6)
	s_nop 1
	v_mov_b32_e32 v124, v164
	v_mov_b32_e32 v125, v165
	global_load_dwordx2 v[164:165], v175, s[80:81] offset:288
	v_lshlrev_b32_e32 v154, 16, v124
	v_and_b32_e32 v155, 0xffff0000, v124
	v_lshlrev_b32_e32 v124, 16, v125
	v_and_b32_e32 v125, 0xffff0000, v125
	v_or_b32_e32 v126, 0x100, v152
	v_mov_b32_e32 v127, v153
	v_pk_add_f32 v[122:123], v[122:123], v[124:125]
	v_pk_add_f32 v[120:121], v[120:121], v[154:155]
	v_lshl_add_u64 v[126:127], s[80:81], 0, v[126:127]
	global_store_dwordx4 v[156:157], v[120:123], off offset:64 nt
	s_waitcnt vmcnt(7)
	s_nop 1
	v_mov_b32_e32 v120, v166
	v_mov_b32_e32 v121, v167
	v_add_u32_e32 v175, 0x20000, v174
	global_load_dwordx2 v[166:167], v175, s[80:81]
	v_or_b32_e32 v152, 0x120, v152
	v_lshl_add_u64 v[122:123], s[80:81], 0, v[152:153]
	v_lshlrev_b32_e32 v124, 16, v120
	v_and_b32_e32 v125, 0xffff0000, v120
	v_lshlrev_b32_e32 v120, 16, v121
	v_and_b32_e32 v121, 0xffff0000, v121
	v_pk_add_f32 v[118:119], v[118:119], v[120:121]
	v_pk_add_f32 v[116:117], v[116:117], v[124:125]
	global_store_dwordx4 v[156:157], v[116:119], off offset:512 nt
	s_waitcnt vmcnt(8)
	s_nop 1
	v_mov_b32_e32 v116, v168
	v_mov_b32_e32 v117, v169
	global_load_dwordx2 v[168:169], v175, s[80:81] offset:32
	v_lshlrev_b32_e32 v124, 16, v116
	v_or_b32_e32 v118, 16, v144
	v_ashrrev_i32_e32 v119, 31, v118
	v_lshlrev_b64 v[118:119], 11, v[118:119]
	v_lshl_add_u64 v[118:119], v[118:119], 0, v[142:143]
	v_and_b32_e32 v125, 0xffff0000, v116
	v_lshlrev_b32_e32 v116, 16, v117
	v_and_b32_e32 v117, 0xffff0000, v117
	v_lshlrev_b64 v[120:121], 1, v[118:119]
	v_pk_add_f32 v[114:115], v[114:115], v[116:117]
	v_pk_add_f32 v[112:113], v[112:113], v[124:125]
	v_lshl_add_u64 v[122:123], s[80:81], 0, v[120:121]
	global_store_dwordx4 v[156:157], v[112:115], off offset:576 nt
	s_waitcnt vmcnt(9)
	s_nop 1
	v_mov_b32_e32 v112, v170
	v_mov_b32_e32 v113, v171
	global_load_dwordx2 v[170:171], v175, s[80:81] offset:256
	v_or_b32_e32 v116, 32, v120
	v_lshl_add_u64 v[114:115], v[118:119], 2, s[88:89]
	v_mov_b32_e32 v117, v121
	v_lshl_add_u64 v[116:117], s[80:81], 0, v[116:117]
	v_lshlrev_b32_e32 v118, 16, v112
	v_and_b32_e32 v119, 0xffff0000, v112
	v_lshlrev_b32_e32 v112, 16, v113
	v_and_b32_e32 v113, 0xffff0000, v113
	v_pk_add_f32 v[110:111], v[110:111], v[112:113]
	v_pk_add_f32 v[108:109], v[108:109], v[118:119]
	global_store_dwordx4 v[114:115], v[108:111], off nt
	s_waitcnt vmcnt(10)
	s_nop 1
	v_mov_b32_e32 v108, v172
	v_mov_b32_e32 v109, v173
	global_load_dwordx2 v[172:173], v175, s[80:81] offset:288
	v_lshlrev_b32_e32 v112, 16, v108
	v_and_b32_e32 v113, 0xffff0000, v108
	v_lshlrev_b32_e32 v108, 16, v109
	v_and_b32_e32 v109, 0xffff0000, v109
	v_or_b32_e32 v110, 0x100, v120
	v_mov_b32_e32 v111, v121
	v_pk_add_f32 v[106:107], v[106:107], v[108:109]
	v_pk_add_f32 v[104:105], v[104:105], v[112:113]
	v_lshl_add_u64 v[110:111], s[80:81], 0, v[110:111]
	global_store_dwordx4 v[114:115], v[104:107], off offset:64 nt
	s_waitcnt vmcnt(11)
	s_nop 1
	v_mov_b32_e32 v104, v162
	v_mov_b32_e32 v105, v163
	v_add_u32_e32 v175, 0x30000, v174
	global_load_dwordx2 v[162:163], v175, s[80:81]
	v_or_b32_e32 v120, 0x120, v120
	v_lshl_add_u64 v[106:107], s[80:81], 0, v[120:121]
	v_lshlrev_b32_e32 v108, 16, v104
	v_and_b32_e32 v109, 0xffff0000, v104
	v_lshlrev_b32_e32 v104, 16, v105
	v_and_b32_e32 v105, 0xffff0000, v105
	v_pk_add_f32 v[102:103], v[102:103], v[104:105]
	v_pk_add_f32 v[100:101], v[100:101], v[108:109]
	global_store_dwordx4 v[114:115], v[100:103], off offset:512 nt
	s_waitcnt vmcnt(11)
	s_nop 1
	v_mov_b32_e32 v100, v164
	v_mov_b32_e32 v101, v165
	global_load_dwordx2 v[164:165], v175, s[80:81] offset:32
	v_lshlrev_b32_e32 v108, 16, v100
	v_or_b32_e32 v102, 32, v144
	v_ashrrev_i32_e32 v103, 31, v102
	v_lshlrev_b64 v[102:103], 11, v[102:103]
	v_lshl_add_u64 v[102:103], v[102:103], 0, v[142:143]
	v_and_b32_e32 v109, 0xffff0000, v100
	v_lshlrev_b32_e32 v100, 16, v101
	v_and_b32_e32 v101, 0xffff0000, v101
	v_lshlrev_b64 v[104:105], 1, v[102:103]
	v_pk_add_f32 v[98:99], v[98:99], v[100:101]
	v_pk_add_f32 v[96:97], v[96:97], v[108:109]
	v_lshl_add_u64 v[106:107], s[80:81], 0, v[104:105]
	global_store_dwordx4 v[114:115], v[96:99], off offset:576 nt
	s_waitcnt vmcnt(11)
; __device__ __forceinline__ unsigned cvt_pk_bf16(float lo, float hi) { return ::cvtpk(lo, hi); }
;     __device__ __forceinline__ void operator()(const f32x4 (&acc)[2][2][4][2], const Unit& u, int wr, int wc, int fr, int fq, int) const {
;         const int row0 = u.pm * BM + wr * 64 + fr, col0 = u.pn * BM + wc * 32 + 4 * fq;
; #pragma unroll
;         for (int ai = 0; ai < 2; ++ai)
; #pragma unroll
;             for (int m = 0; m < 4; ++m) { const int row = row0 + ai * HALF + m * 16; const size_t off = (size_t)row * 2048 + col0; float s = 0.f;
; #pragma unroll
;                 for (int bj = 0; bj < 2; ++bj)
; #pragma unroll
;                     for (int n = 0; n < 2; ++n) { const size_t o2 = off + bj * HALF + n * 16; f32x4 bs;
;                         if (MODE == 0) bs = __builtin_nontemporal_load((const f32x4*)(base + o2));
;                         else { const u32x2 b2 = *(const u32x2*)(xb + o2); bs[0] = __builtin_bit_cast(float, b2.x << 16); bs[1] = __builtin_bit_cast(float, b2.x & 0xffff0000u); bs[2] = __builtin_bit_cast(float, b2.y << 16); bs[3] = __builtin_bit_cast(float, b2.y & 0xffff0000u); }
;                         const f32x4 o = bs + acc[ai][bj][m][n];
;                         if (MODE == 2) __builtin_nontemporal_store(o, (f32x4*)(out + o2));
;                         else { s += (o[0] * o[0] + o[1] * o[1]) + (o[2] * o[2] + o[3] * o[3]); u32x2 w; w.x = cvt_pk_bf16(o[0], o[1]); w.y = cvt_pk_bf16(o[2], o[3]); *(u32x2*)(xb + o2) = w; } }
	s_nop 1
	v_mov_b32_e32 v96, v166
	v_mov_b32_e32 v97, v167
	global_load_dwordx2 v[166:167], v175, s[80:81] offset:256
	v_or_b32_e32 v100, 32, v104
	v_lshl_add_u64 v[98:99], v[102:103], 2, s[88:89]
	v_mov_b32_e32 v101, v105
	v_lshl_add_u64 v[100:101], s[80:81], 0, v[100:101]
	v_lshlrev_b32_e32 v102, 16, v96
	v_and_b32_e32 v103, 0xffff0000, v96
	v_lshlrev_b32_e32 v96, 16, v97
	v_and_b32_e32 v97, 0xffff0000, v97
	v_pk_add_f32 v[94:95], v[94:95], v[96:97]
	v_pk_add_f32 v[92:93], v[92:93], v[102:103]
	global_store_dwordx4 v[98:99], v[92:95], off nt
	s_waitcnt vmcnt(11)
	s_nop 1
	v_mov_b32_e32 v92, v168
	v_mov_b32_e32 v93, v169
	global_load_dwordx2 v[168:169], v175, s[80:81] offset:288
	v_lshlrev_b32_e32 v96, 16, v92
	v_and_b32_e32 v97, 0xffff0000, v92
	v_lshlrev_b32_e32 v92, 16, v93
	v_and_b32_e32 v93, 0xffff0000, v93
	v_or_b32_e32 v94, 0x100, v104
	v_mov_b32_e32 v95, v105
	v_pk_add_f32 v[90:91], v[90:91], v[92:93]
	v_pk_add_f32 v[88:89], v[88:89], v[96:97]
	v_lshl_add_u64 v[94:95], s[80:81], 0, v[94:95]
	global_store_dwordx4 v[98:99], v[88:91], off offset:64 nt
	s_waitcnt vmcnt(11)
	s_nop 1
	v_mov_b32_e32 v88, v170
	v_mov_b32_e32 v89, v171
	v_add_u32_e32 v175, 0x80000, v174
	global_load_dwordx2 v[170:171], v175, s[80:81]
	v_or_b32_e32 v104, 0x120, v104
	v_lshl_add_u64 v[90:91], s[80:81], 0, v[104:105]
	v_lshlrev_b32_e32 v92, 16, v88
	v_and_b32_e32 v93, 0xffff0000, v88
	v_lshlrev_b32_e32 v88, 16, v89
	v_and_b32_e32 v89, 0xffff0000, v89
	v_pk_add_f32 v[86:87], v[86:87], v[88:89]
	v_pk_add_f32 v[84:85], v[84:85], v[92:93]
	global_store_dwordx4 v[98:99], v[84:87], off offset:512 nt
	s_waitcnt vmcnt(11)
	s_nop 1
	v_mov_b32_e32 v84, v172
	v_mov_b32_e32 v85, v173
	global_load_dwordx2 v[172:173], v175, s[80:81] offset:32
	v_lshlrev_b32_e32 v92, 16, v84
	v_or_b32_e32 v86, 48, v144
	v_ashrrev_i32_e32 v87, 31, v86
	v_lshlrev_b64 v[86:87], 11, v[86:87]
	v_lshl_add_u64 v[86:87], v[86:87], 0, v[142:143]
	v_and_b32_e32 v93, 0xffff0000, v84
	v_lshlrev_b32_e32 v84, 16, v85
	v_and_b32_e32 v85, 0xffff0000, v85
	v_lshlrev_b64 v[88:89], 1, v[86:87]
	v_pk_add_f32 v[82:83], v[82:83], v[84:85]
	v_pk_add_f32 v[80:81], v[80:81], v[92:93]
	v_lshl_add_u64 v[90:91], s[80:81], 0, v[88:89]
	global_store_dwordx4 v[98:99], v[80:83], off offset:576 nt
	s_waitcnt vmcnt(11)
	s_nop 1
	v_mov_b32_e32 v80, v162
	v_mov_b32_e32 v81, v163
	global_load_dwordx2 v[162:163], v175, s[80:81] offset:256
	v_or_b32_e32 v84, 32, v88
	v_lshl_add_u64 v[82:83], v[86:87], 2, s[88:89]
	v_mov_b32_e32 v85, v89
	v_lshl_add_u64 v[84:85], s[80:81], 0, v[84:85]
	v_lshlrev_b32_e32 v86, 16, v80
	v_and_b32_e32 v87, 0xffff0000, v80
	v_lshlrev_b32_e32 v80, 16, v81
	v_and_b32_e32 v81, 0xffff0000, v81
	v_pk_add_f32 v[78:79], v[78:79], v[80:81]
	v_pk_add_f32 v[76:77], v[76:77], v[86:87]
	global_store_dwordx4 v[82:83], v[76:79], off nt
	s_waitcnt vmcnt(11)
	s_nop 1
	v_mov_b32_e32 v76, v164
	v_mov_b32_e32 v77, v165
	global_load_dwordx2 v[164:165], v175, s[80:81] offset:288
	v_lshlrev_b32_e32 v80, 16, v76
	v_and_b32_e32 v81, 0xffff0000, v76
	v_lshlrev_b32_e32 v76, 16, v77
	v_and_b32_e32 v77, 0xffff0000, v77
	v_or_b32_e32 v78, 0x100, v88
	v_mov_b32_e32 v79, v89
	v_pk_add_f32 v[74:75], v[74:75], v[76:77]
	v_pk_add_f32 v[72:73], v[72:73], v[80:81]
	v_lshl_add_u64 v[78:79], s[80:81], 0, v[78:79]
	global_store_dwordx4 v[82:83], v[72:75], off offset:64 nt
	s_waitcnt vmcnt(11)
	s_nop 1
	v_mov_b32_e32 v72, v166
	v_mov_b32_e32 v73, v167
	v_add_u32_e32 v175, 0x90000, v174
	global_load_dwordx2 v[166:167], v175, s[80:81]
	v_or_b32_e32 v88, 0x120, v88
	v_lshl_add_u64 v[74:75], s[80:81], 0, v[88:89]
	v_lshlrev_b32_e32 v76, 16, v72
	v_and_b32_e32 v77, 0xffff0000, v72
	v_lshlrev_b32_e32 v72, 16, v73
	v_and_b32_e32 v73, 0xffff0000, v73
	v_pk_add_f32 v[70:71], v[70:71], v[72:73]
	v_pk_add_f32 v[68:69], v[68:69], v[76:77]
	global_store_dwordx4 v[82:83], v[68:71], off offset:512 nt
	s_waitcnt vmcnt(11)
	s_nop 1
	v_mov_b32_e32 v68, v168
	v_mov_b32_e32 v69, v169
	global_load_dwordx2 v[168:169], v175, s[80:81] offset:32
	v_lshlrev_b32_e32 v76, 16, v68
	v_lshl_add_u64 v[70:71], v[140:141], 0, s[10:11]
	v_and_b32_e32 v77, 0xffff0000, v68
	v_lshlrev_b32_e32 v68, 16, v69
	v_and_b32_e32 v69, 0xffff0000, v69
	v_lshlrev_b64 v[72:73], 1, v[70:71]
	v_pk_add_f32 v[66:67], v[66:67], v[68:69]
	v_pk_add_f32 v[64:65], v[64:65], v[76:77]
	v_lshl_add_u64 v[74:75], s[80:81], 0, v[72:73]
	global_store_dwordx4 v[82:83], v[64:67], off offset:576 nt
	s_waitcnt vmcnt(11)
	s_nop 1
	v_mov_b32_e32 v64, v170
	v_mov_b32_e32 v65, v171
	global_load_dwordx2 v[170:171], v175, s[80:81] offset:256
	v_or_b32_e32 v68, 32, v72
	v_lshl_add_u64 v[66:67], v[70:71], 2, s[88:89]
	v_mov_b32_e32 v69, v73
	v_lshl_add_u64 v[68:69], s[80:81], 0, v[68:69]
	v_lshlrev_b32_e32 v70, 16, v64
	v_and_b32_e32 v71, 0xffff0000, v64
	v_lshlrev_b32_e32 v64, 16, v65
	v_and_b32_e32 v65, 0xffff0000, v65
	v_pk_add_f32 v[62:63], v[62:63], v[64:65]
	v_pk_add_f32 v[60:61], v[60:61], v[70:71]
	global_store_dwordx4 v[66:67], v[60:63], off nt
	s_waitcnt vmcnt(11)
	s_nop 1
	v_mov_b32_e32 v60, v172
	v_mov_b32_e32 v61, v173
	global_load_dwordx2 v[172:173], v175, s[80:81] offset:288
	v_lshlrev_b32_e32 v64, 16, v60
	v_and_b32_e32 v65, 0xffff0000, v60
	v_lshlrev_b32_e32 v60, 16, v61
	v_and_b32_e32 v61, 0xffff0000, v61
	v_or_b32_e32 v62, 0x100, v72
	v_mov_b32_e32 v63, v73
	v_pk_add_f32 v[58:59], v[58:59], v[60:61]
	v_pk_add_f32 v[56:57], v[56:57], v[64:65]
	v_lshl_add_u64 v[62:63], s[80:81], 0, v[62:63]
	global_store_dwordx4 v[66:67], v[56:59], off offset:64 nt
	s_waitcnt vmcnt(11)
; __device__ __forceinline__ unsigned cvt_pk_bf16(float lo, float hi) { return ::cvtpk(lo, hi); }
;     __device__ __forceinline__ void operator()(const f32x4 (&acc)[2][2][4][2], const Unit& u, int wr, int wc, int fr, int fq, int) const {
;         const int row0 = u.pm * BM + wr * 64 + fr, col0 = u.pn * BM + wc * 32 + 4 * fq;
; #pragma unroll
;         for (int ai = 0; ai < 2; ++ai)
; #pragma unroll
;             for (int m = 0; m < 4; ++m) { const int row = row0 + ai * HALF + m * 16; const size_t off = (size_t)row * 2048 + col0; float s = 0.f;
; #pragma unroll
;                 for (int bj = 0; bj < 2; ++bj)
; #pragma unroll
;                     for (int n = 0; n < 2; ++n) { const size_t o2 = off + bj * HALF + n * 16; f32x4 bs;
;                         if (MODE == 0) bs = __builtin_nontemporal_load((const f32x4*)(base + o2));
;                         else { const u32x2 b2 = *(const u32x2*)(xb + o2); bs[0] = __builtin_bit_cast(float, b2.x << 16); bs[1] = __builtin_bit_cast(float, b2.x & 0xffff0000u); bs[2] = __builtin_bit_cast(float, b2.y << 16); bs[3] = __builtin_bit_cast(float, b2.y & 0xffff0000u); }
;                         const f32x4 o = bs + acc[ai][bj][m][n];
;                         if (MODE == 2) __builtin_nontemporal_store(o, (f32x4*)(out + o2));
;                         else { s += (o[0] * o[0] + o[1] * o[1]) + (o[2] * o[2] + o[3] * o[3]); u32x2 w; w.x = cvt_pk_bf16(o[0], o[1]); w.y = cvt_pk_bf16(o[2], o[3]); *(u32x2*)(xb + o2) = w; } }
	s_nop 1
	v_mov_b32_e32 v56, v162
	v_mov_b32_e32 v57, v163
	v_add_u32_e32 v175, 0xa0000, v174
	global_load_dwordx2 v[162:163], v175, s[80:81]
	v_or_b32_e32 v72, 0x120, v72
	v_lshl_add_u64 v[58:59], s[80:81], 0, v[72:73]
	v_lshlrev_b32_e32 v60, 16, v56
	v_and_b32_e32 v61, 0xffff0000, v56
	v_lshlrev_b32_e32 v56, 16, v57
	v_and_b32_e32 v57, 0xffff0000, v57
	v_pk_add_f32 v[54:55], v[54:55], v[56:57]
	v_pk_add_f32 v[52:53], v[52:53], v[60:61]
	global_store_dwordx4 v[66:67], v[52:55], off offset:512 nt
	s_waitcnt vmcnt(11)
	s_nop 1
	v_mov_b32_e32 v52, v164
	v_mov_b32_e32 v53, v165
	global_load_dwordx2 v[164:165], v175, s[80:81] offset:32
	v_lshlrev_b32_e32 v60, 16, v52
	v_lshl_add_u64 v[54:55], v[140:141], 0, s[12:13]
	v_and_b32_e32 v61, 0xffff0000, v52
	v_lshlrev_b32_e32 v52, 16, v53
	v_and_b32_e32 v53, 0xffff0000, v53
	v_lshlrev_b64 v[56:57], 1, v[54:55]
	v_pk_add_f32 v[50:51], v[50:51], v[52:53]
	v_pk_add_f32 v[48:49], v[48:49], v[60:61]
	v_lshl_add_u64 v[58:59], s[80:81], 0, v[56:57]
	global_store_dwordx4 v[66:67], v[48:51], off offset:576 nt
	s_waitcnt vmcnt(11)
	s_nop 1
	v_mov_b32_e32 v48, v166
	v_mov_b32_e32 v49, v167
	global_load_dwordx2 v[166:167], v175, s[80:81] offset:256
	v_or_b32_e32 v52, 32, v56
	v_lshl_add_u64 v[50:51], v[54:55], 2, s[88:89]
	v_mov_b32_e32 v53, v57
	v_lshl_add_u64 v[52:53], s[80:81], 0, v[52:53]
	v_lshlrev_b32_e32 v54, 16, v48
	v_and_b32_e32 v55, 0xffff0000, v48
	v_lshlrev_b32_e32 v48, 16, v49
	v_and_b32_e32 v49, 0xffff0000, v49
	v_pk_add_f32 v[46:47], v[46:47], v[48:49]
	v_pk_add_f32 v[44:45], v[44:45], v[54:55]
	global_store_dwordx4 v[50:51], v[44:47], off nt
	s_waitcnt vmcnt(11)
	s_nop 1
	v_mov_b32_e32 v44, v168
	v_mov_b32_e32 v45, v169
	global_load_dwordx2 v[168:169], v175, s[80:81] offset:288
	v_lshlrev_b32_e32 v48, 16, v44
	v_and_b32_e32 v49, 0xffff0000, v44
	v_lshlrev_b32_e32 v44, 16, v45
	v_and_b32_e32 v45, 0xffff0000, v45
	v_or_b32_e32 v46, 0x100, v56
	v_mov_b32_e32 v47, v57
	v_pk_add_f32 v[42:43], v[42:43], v[44:45]
	v_pk_add_f32 v[40:41], v[40:41], v[48:49]
	v_lshl_add_u64 v[46:47], s[80:81], 0, v[46:47]
	global_store_dwordx4 v[50:51], v[40:43], off offset:64 nt
	s_waitcnt vmcnt(11)
	s_nop 1
	v_mov_b32_e32 v40, v170
	v_mov_b32_e32 v41, v171
	v_add_u32_e32 v175, 0xb0000, v174
	global_load_dwordx2 v[170:171], v175, s[80:81]
	v_or_b32_e32 v56, 0x120, v56
	v_lshl_add_u64 v[42:43], s[80:81], 0, v[56:57]
	v_lshlrev_b32_e32 v44, 16, v40
	v_and_b32_e32 v45, 0xffff0000, v40
	v_lshlrev_b32_e32 v40, 16, v41
	v_and_b32_e32 v41, 0xffff0000, v41
	v_pk_add_f32 v[38:39], v[38:39], v[40:41]
	v_pk_add_f32 v[36:37], v[36:37], v[44:45]
	global_store_dwordx4 v[50:51], v[36:39], off offset:512 nt
	s_waitcnt vmcnt(11)
	s_nop 1
	v_mov_b32_e32 v36, v172
	v_mov_b32_e32 v37, v173
	global_load_dwordx2 v[172:173], v175, s[80:81] offset:32
	v_lshlrev_b32_e32 v44, 16, v36
	v_lshl_add_u64 v[38:39], v[140:141], 0, s[14:15]
	v_and_b32_e32 v45, 0xffff0000, v36
	v_lshlrev_b32_e32 v36, 16, v37
	v_and_b32_e32 v37, 0xffff0000, v37
	v_lshlrev_b64 v[40:41], 1, v[38:39]
	v_pk_add_f32 v[34:35], v[34:35], v[36:37]
	v_pk_add_f32 v[32:33], v[32:33], v[44:45]
	v_lshl_add_u64 v[42:43], s[80:81], 0, v[40:41]
	global_store_dwordx4 v[50:51], v[32:35], off offset:576 nt
	s_waitcnt vmcnt(11)
	s_nop 1
	v_mov_b32_e32 v32, v162
	v_mov_b32_e32 v33, v163
	global_load_dwordx2 v[162:163], v175, s[80:81] offset:256
	v_or_b32_e32 v36, 32, v40
	v_lshl_add_u64 v[34:35], v[38:39], 2, s[88:89]
	v_mov_b32_e32 v37, v41
	v_lshl_add_u64 v[36:37], s[80:81], 0, v[36:37]
	v_lshlrev_b32_e32 v38, 16, v32
	v_and_b32_e32 v39, 0xffff0000, v32
	v_lshlrev_b32_e32 v32, 16, v33
	v_and_b32_e32 v33, 0xffff0000, v33
	v_pk_add_f32 v[30:31], v[30:31], v[32:33]
	v_pk_add_f32 v[28:29], v[28:29], v[38:39]
	global_store_dwordx4 v[34:35], v[28:31], off nt
	s_waitcnt vmcnt(11)
	s_nop 1
	v_mov_b32_e32 v28, v164
	v_mov_b32_e32 v29, v165
	global_load_dwordx2 v[164:165], v175, s[80:81] offset:288
	v_lshlrev_b32_e32 v32, 16, v28
	v_and_b32_e32 v33, 0xffff0000, v28
	v_lshlrev_b32_e32 v28, 16, v29
	v_and_b32_e32 v29, 0xffff0000, v29
	v_or_b32_e32 v30, 0x100, v40
	v_mov_b32_e32 v31, v41
	v_pk_add_f32 v[26:27], v[26:27], v[28:29]
	v_pk_add_f32 v[24:25], v[24:25], v[32:33]
	v_lshl_add_u64 v[30:31], s[80:81], 0, v[30:31]
	global_store_dwordx4 v[34:35], v[24:27], off offset:64 nt
	s_waitcnt vmcnt(11)
	s_nop 1
	v_mov_b32_e32 v24, v166
	v_mov_b32_e32 v25, v167
	v_or_b32_e32 v40, 0x120, v40
	v_lshl_add_u64 v[26:27], s[80:81], 0, v[40:41]
	v_lshlrev_b32_e32 v28, 16, v24
	v_and_b32_e32 v29, 0xffff0000, v24
	v_lshlrev_b32_e32 v24, 16, v25
	v_and_b32_e32 v25, 0xffff0000, v25
	v_pk_add_f32 v[22:23], v[22:23], v[24:25]
	v_pk_add_f32 v[20:21], v[20:21], v[28:29]
	global_store_dwordx4 v[34:35], v[20:23], off offset:512 nt
	s_waitcnt vmcnt(10)
	s_nop 1
	v_mov_b32_e32 v20, v168
	v_mov_b32_e32 v21, v169
	v_lshlrev_b32_e32 v28, 16, v20
	v_lshl_add_u64 v[22:23], v[140:141], 0, s[16:17]
	v_and_b32_e32 v29, 0xffff0000, v20
	v_lshlrev_b32_e32 v20, 16, v21
	v_and_b32_e32 v21, 0xffff0000, v21
	v_lshlrev_b64 v[24:25], 1, v[22:23]
	v_pk_add_f32 v[18:19], v[18:19], v[20:21]
	v_pk_add_f32 v[16:17], v[16:17], v[28:29]
	v_lshl_add_u64 v[26:27], s[80:81], 0, v[24:25]
	global_store_dwordx4 v[34:35], v[16:19], off offset:576 nt
	s_waitcnt vmcnt(9)
	s_nop 1
	v_mov_b32_e32 v16, v170
	v_mov_b32_e32 v17, v171
	v_or_b32_e32 v20, 32, v24
	v_lshl_add_u64 v[18:19], v[22:23], 2, s[88:89]
	v_mov_b32_e32 v21, v25
	v_lshl_add_u64 v[20:21], s[80:81], 0, v[20:21]
	v_lshlrev_b32_e32 v22, 16, v16
	v_and_b32_e32 v23, 0xffff0000, v16
	v_lshlrev_b32_e32 v16, 16, v17
	v_and_b32_e32 v17, 0xffff0000, v17
	v_pk_add_f32 v[14:15], v[14:15], v[16:17]
	v_pk_add_f32 v[12:13], v[12:13], v[22:23]
	global_store_dwordx4 v[18:19], v[12:15], off nt
	s_waitcnt vmcnt(8)
	s_nop 1
	v_mov_b32_e32 v12, v172
	v_mov_b32_e32 v13, v173
	v_lshlrev_b32_e32 v16, 16, v12
	v_and_b32_e32 v17, 0xffff0000, v12
	v_lshlrev_b32_e32 v12, 16, v13
	v_and_b32_e32 v13, 0xffff0000, v13
	v_or_b32_e32 v14, 0x100, v24
	v_mov_b32_e32 v15, v25
	v_pk_add_f32 v[10:11], v[10:11], v[12:13]
	v_pk_add_f32 v[8:9], v[8:9], v[16:17]
	v_lshl_add_u64 v[14:15], s[80:81], 0, v[14:15]
	global_store_dwordx4 v[18:19], v[8:11], off offset:64 nt
	s_waitcnt vmcnt(7)
	s_nop 1
	v_mov_b32_e32 v8, v162
	v_mov_b32_e32 v9, v163
	v_or_b32_e32 v24, 0x120, v24
	v_lshl_add_u64 v[10:11], s[80:81], 0, v[24:25]
	v_lshlrev_b32_e32 v12, 16, v8
	v_and_b32_e32 v13, 0xffff0000, v8
	v_lshlrev_b32_e32 v8, 16, v9
	v_and_b32_e32 v9, 0xffff0000, v9
	v_pk_add_f32 v[6:7], v[6:7], v[8:9]
	v_pk_add_f32 v[4:5], v[4:5], v[12:13]
	global_store_dwordx4 v[18:19], v[4:7], off offset:512 nt
	s_waitcnt vmcnt(6)
	s_nop 1
	v_mov_b32_e32 v4, v164
	v_mov_b32_e32 v5, v165
	v_lshlrev_b32_e32 v6, 16, v4
	v_and_b32_e32 v7, 0xffff0000, v4
	v_lshlrev_b32_e32 v4, 16, v5
	v_and_b32_e32 v5, 0xffff0000, v5
	v_pk_add_f32 v[2:3], v[2:3], v[4:5]
	v_pk_add_f32 v[0:1], v[0:1], v[6:7]
	global_store_dwordx4 v[18:19], v[0:3], off offset:576 nt
	s_cbranch_vccnz .LBB0_1944
; #define PG8_BAR __builtin_amdgcn_s_barrier()
; template <class Epi, class Sched, bool ALIGN_EPI = false, bool SP2 = false>
; __device__ __forceinline__ void gemm_phase(PG8_LAS unsigned char* lds, const Gemm g, const Sched& S, const Epi& E) {
;     ...
;         cur = nxt; cA = nA; cB = nB; ++ui;
;         if constexpr (ALIGN_EPI) { if (wr == 1) PG8_BAR; }
;     }
	s_andn2_b64 vcc, exec, s[2:3]
	s_cbranch_vccnz .LBB0_1943
	s_barrier
	s_branch .LBB0_1943
